# epilogue load-ladder de-serialisation: the 8 ssq row-statistic loads of the SwiGLU (FFN1/FFN2 up) and bf16-scale (in-proj, XQ) GEMM epilogues are issued together into dead MFMA-operand registers and w
# speedup vs baseline: 1.0189x; 1.0055x over previous
; __device__ __forceinline__ float row_rstd16_coop(const float* ssq, int row, int fq, float inv_n) {
;     const f32x4 a = *(const f32x4*)(ssq + (size_t)row * 16 + fq * 4);
;     float s = (a[0] + a[1]) + (a[2] + a[3]);
;     s += __shfl_xor(s, 16); s += __shfl_xor(s, 32);
;     return __builtin_amdgcn_rsqf(s * inv_n + EPS);
;     __device__ __forceinline__ void operator()(const f32x4 (&acc)[2][2][4][2], const Unit& u, int wr, int wc, int fr, int fq) const {
;     ...
;         for (int ai = 0; ai < 2; ++ai) {
; #pragma unroll
;             for (int m = 0; m < 4; ++m) rsv[ai][m] = row_rstd16_coop(ssq, row0 + ai * HALF + m * 16, fq, 1.0f / 1024.0f);
;         }
; #pragma unroll
;         for (int ai = 0; ai < 2; ++ai)
; #pragma unroll
;             for (int m = 0; m < 4; ++m) {
;                 const int row = row0 + ai * HALF + m * 16;
;                 const float rs = rsv[ai][m];
;                 bf16_t* rowp = H + (size_t)row * ldh + (col0 >> 1);
; #pragma unroll
;                 for (int bj = 0; bj < 2; ++bj) {
;                     const f32x4 v0 = acc[ai][bj][m][0] * rs, v1 = acc[ai][bj][m][1] * rs;
.LBB0_3168:
	v_lshl_add_u32 v156, s58, 8, v1
	v_ashrrev_i32_e32 v157, 31, v156
	v_lshlrev_b64 v[130:131], 6, v[156:157]
	v_lshl_add_u64 v[130:131], v[142:143], 0, v[130:131]
	global_load_dwordx4 v[182:185], v[130:131], off offset:1024
	global_load_dwordx4 v[186:189], v[130:131], off offset:2048
	global_load_dwordx4 v[190:193], v[130:131], off offset:3072
	v_add_co_u32_e32 v210, vcc, 0x2000, v130
	s_nop 1
	v_addc_co_u32_e32 v211, vcc, 0, v131, vcc
	global_load_dwordx4 v[194:197], v[210:211], off
	global_load_dwordx4 v[198:201], v[210:211], off offset:1024
	global_load_dwordx4 v[202:205], v[210:211], off offset:2048
	global_load_dwordx4 v[206:209], v[210:211], off offset:3072
	global_load_dwordx4 v[130:133], v[130:131], off
	v_or_b32_e32 v174, 16, v156
	v_ashrrev_i32_e32 v175, 31, v174
	v_or_b32_e32 v170, 32, v156
	v_ashrrev_i32_e32 v171, 31, v170
	v_or_b32_e32 v166, 48, v156
	v_ashrrev_i32_e32 v167, 31, v166
	v_add_u32_e32 v162, 0x80, v156
	v_ashrrev_i32_e32 v163, 31, v162
	v_add_u32_e32 v158, 0x90, v156
	v_ashrrev_i32_e32 v159, 31, v158
	v_add_u32_e32 v152, 0xa0, v156
	v_ashrrev_i32_e32 v153, 31, v152
	s_and_b64 vcc, exec, s[4:5]
	s_waitcnt vmcnt(0)
	v_mov_b32_e32 v148, v131
	v_mov_b32_e32 v149, v132
	v_mov_b32_e32 v131, v133
	v_pk_add_f32 v[130:131], v[148:149], v[130:131]
	s_nop 0
	v_add_f32_e32 v130, v130, v131
	ds_bpermute_b32 v131, v221, v130
	s_waitcnt lgkmcnt(0)
	v_add_f32_e32 v130, v130, v131
	ds_bpermute_b32 v131, v222, v130
	s_waitcnt lgkmcnt(0)
	v_add_f32_e32 v130, v130, v131
	v_fmamk_f32 v130, v130, 0x3a800000, v231
	v_rsq_f32_e32 v176, v130
	s_nop 1
	v_pk_mul_f32 v[122:123], v[122:123], v[176:177] op_sel_hi:[1,0]
	v_pk_mul_f32 v[124:125], v[124:125], v[176:177] op_sel_hi:[1,0]
	v_pk_mul_f32 v[126:127], v[126:127], v[176:177] op_sel_hi:[1,0]
	v_pk_mul_f32 v[128:129], v[128:129], v[176:177] op_sel_hi:[1,0]
	v_pk_mul_f32 v[118:119], v[118:119], v[176:177] op_sel_hi:[1,0]
	v_pk_mul_f32 v[120:121], v[120:121], v[176:177] op_sel_hi:[1,0]
	v_pk_mul_f32 v[114:115], v[114:115], v[176:177] op_sel_hi:[1,0]
	v_pk_mul_f32 v[116:117], v[116:117], v[176:177] op_sel_hi:[1,0]
	v_add_f32_e32 v130, v183, v182
	v_add_f32_e32 v131, v184, v185
	s_nop 0
	v_add_f32_e32 v130, v130, v131
	ds_bpermute_b32 v131, v221, v130
	s_waitcnt lgkmcnt(0)
	v_add_f32_e32 v130, v130, v131
	ds_bpermute_b32 v131, v222, v130
	s_waitcnt lgkmcnt(0)
	v_add_f32_e32 v130, v130, v131
	v_fmamk_f32 v130, v130, 0x3a800000, v231
	v_rsq_f32_e32 v172, v130
	s_nop 1
	v_pk_mul_f32 v[110:111], v[110:111], v[172:173] op_sel_hi:[1,0]
	v_pk_mul_f32 v[112:113], v[112:113], v[172:173] op_sel_hi:[1,0]
	v_pk_mul_f32 v[106:107], v[106:107], v[172:173] op_sel_hi:[1,0]
	v_pk_mul_f32 v[108:109], v[108:109], v[172:173] op_sel_hi:[1,0]
	v_pk_mul_f32 v[102:103], v[102:103], v[172:173] op_sel_hi:[1,0]
	v_pk_mul_f32 v[104:105], v[104:105], v[172:173] op_sel_hi:[1,0]
	v_pk_mul_f32 v[98:99], v[98:99], v[172:173] op_sel_hi:[1,0]
	v_pk_mul_f32 v[100:101], v[100:101], v[172:173] op_sel_hi:[1,0]
	v_add_f32_e32 v130, v187, v186
	v_add_f32_e32 v131, v188, v189
	s_nop 0
	v_add_f32_e32 v130, v130, v131
	ds_bpermute_b32 v131, v221, v130
	s_waitcnt lgkmcnt(0)
	v_add_f32_e32 v130, v130, v131
	ds_bpermute_b32 v131, v222, v130
	s_waitcnt lgkmcnt(0)
	v_add_f32_e32 v130, v130, v131
	v_fmamk_f32 v130, v130, 0x3a800000, v231
	v_rsq_f32_e32 v168, v130
	s_nop 1
	v_pk_mul_f32 v[94:95], v[94:95], v[168:169] op_sel_hi:[1,0]
	v_pk_mul_f32 v[96:97], v[96:97], v[168:169] op_sel_hi:[1,0]
	v_pk_mul_f32 v[90:91], v[90:91], v[168:169] op_sel_hi:[1,0]
	v_pk_mul_f32 v[92:93], v[92:93], v[168:169] op_sel_hi:[1,0]
	v_pk_mul_f32 v[86:87], v[86:87], v[168:169] op_sel_hi:[1,0]
	v_pk_mul_f32 v[88:89], v[88:89], v[168:169] op_sel_hi:[1,0]
	v_pk_mul_f32 v[82:83], v[82:83], v[168:169] op_sel_hi:[1,0]
	v_pk_mul_f32 v[84:85], v[84:85], v[168:169] op_sel_hi:[1,0]
	v_add_f32_e32 v130, v191, v190
	v_add_f32_e32 v131, v192, v193
	s_nop 0
	v_add_f32_e32 v130, v130, v131
	ds_bpermute_b32 v131, v221, v130
	s_waitcnt lgkmcnt(0)
	v_add_f32_e32 v130, v130, v131
	ds_bpermute_b32 v131, v222, v130
	s_waitcnt lgkmcnt(0)
	v_add_f32_e32 v130, v130, v131
	v_fmamk_f32 v130, v130, 0x3a800000, v231
	v_rsq_f32_e32 v164, v130
	s_nop 1
	v_pk_mul_f32 v[78:79], v[78:79], v[164:165] op_sel_hi:[1,0]
	v_pk_mul_f32 v[80:81], v[80:81], v[164:165] op_sel_hi:[1,0]
	v_pk_mul_f32 v[74:75], v[74:75], v[164:165] op_sel_hi:[1,0]
	v_pk_mul_f32 v[76:77], v[76:77], v[164:165] op_sel_hi:[1,0]
	v_pk_mul_f32 v[70:71], v[70:71], v[164:165] op_sel_hi:[1,0]
	v_pk_mul_f32 v[72:73], v[72:73], v[164:165] op_sel_hi:[1,0]
	v_pk_mul_f32 v[66:67], v[66:67], v[164:165] op_sel_hi:[1,0]
	v_pk_mul_f32 v[68:69], v[68:69], v[164:165] op_sel_hi:[1,0]
	v_add_f32_e32 v130, v195, v194
	v_add_f32_e32 v131, v196, v197
	s_nop 0
	v_add_f32_e32 v130, v130, v131
	ds_bpermute_b32 v131, v221, v130
	s_waitcnt lgkmcnt(0)
	v_add_f32_e32 v130, v130, v131
	ds_bpermute_b32 v131, v222, v130
	s_waitcnt lgkmcnt(0)
	v_add_f32_e32 v130, v130, v131
	v_fmamk_f32 v130, v130, 0x3a800000, v231
	v_rsq_f32_e32 v160, v130
	s_nop 1
	v_pk_mul_f32 v[62:63], v[62:63], v[160:161] op_sel_hi:[1,0]
	v_pk_mul_f32 v[64:65], v[64:65], v[160:161] op_sel_hi:[1,0]
	v_pk_mul_f32 v[58:59], v[58:59], v[160:161] op_sel_hi:[1,0]
	v_pk_mul_f32 v[60:61], v[60:61], v[160:161] op_sel_hi:[1,0]
	v_pk_mul_f32 v[54:55], v[54:55], v[160:161] op_sel_hi:[1,0]
	v_pk_mul_f32 v[56:57], v[56:57], v[160:161] op_sel_hi:[1,0]
	v_pk_mul_f32 v[50:51], v[50:51], v[160:161] op_sel_hi:[1,0]
	v_pk_mul_f32 v[52:53], v[52:53], v[160:161] op_sel_hi:[1,0]
	v_add_f32_e32 v130, v199, v198
	v_add_f32_e32 v131, v200, v201
	s_nop 0
	v_add_f32_e32 v130, v130, v131
	ds_bpermute_b32 v131, v221, v130
	s_waitcnt lgkmcnt(0)
; __device__ __forceinline__ unsigned cvt_pk_bf16(float lo, float hi) { unsigned r; asm volatile("v_cvt_pk_bf16_f32 %0, %1, %2" : "=v"(r) : "v"(lo), "v"(hi)); return r; }
; __device__ __forceinline__ float row_rstd16_coop(const float* ssq, int row, int fq, float inv_n) {
;     const f32x4 a = *(const f32x4*)(ssq + (size_t)row * 16 + fq * 4);
;     float s = (a[0] + a[1]) + (a[2] + a[3]);
;     s += __shfl_xor(s, 16); s += __shfl_xor(s, 32);
;     return __builtin_amdgcn_rsqf(s * inv_n + EPS);
;     __device__ __forceinline__ static float sg(float g, float uu) { return g * __builtin_amdgcn_rcpf(1.0f + __builtin_amdgcn_exp2f(-1.4426950408889634f * g)) * uu; }
;     __device__ __forceinline__ void operator()(const f32x4 (&acc)[2][2][4][2], const Unit& u, int wr, int wc, int fr, int fq) const {
;         const int row0 = u.pm * BM + wr * 64 + fr, col0 = u.pn * BM + wc * 32 + 8 * fq;
;         float rsv[2][4];
; #pragma unroll
;         for (int ai = 0; ai < 2; ++ai) {
; #pragma unroll
;             for (int m = 0; m < 4; ++m) rsv[ai][m] = row_rstd16_coop(ssq, row0 + ai * HALF + m * 16, fq, 1.0f / 1024.0f);
;         }
; #pragma unroll
;         for (int ai = 0; ai < 2; ++ai)
; #pragma unroll
;             for (int m = 0; m < 4; ++m) {
;                 const int row = row0 + ai * HALF + m * 16;
;                 const float rs = rsv[ai][m];
;                 bf16_t* rowp = H + (size_t)row * ldh + (col0 >> 1);
; #pragma unroll
;                 for (int bj = 0; bj < 2; ++bj) {
;                     const f32x4 v0 = acc[ai][bj][m][0] * rs, v1 = acc[ai][bj][m][1] * rs;
;                     u32x2 w; w.x = cvt_pk_bf16(sg(v0[0], v0[1]), sg(v0[2], v0[3])); w.y = cvt_pk_bf16(sg(v1[0], v1[1]), sg(v1[2], v1[3]));
;                     *(u32x2*)(rowp + bj * (HALF / 2)) = w;
;                 }
;             }
	v_add_f32_e32 v130, v130, v131
	ds_bpermute_b32 v131, v222, v130
	s_waitcnt lgkmcnt(0)
	v_add_f32_e32 v130, v130, v131
	v_fmamk_f32 v130, v130, 0x3a800000, v231
	v_rsq_f32_e32 v154, v130
	s_nop 1
	v_pk_mul_f32 v[46:47], v[46:47], v[154:155] op_sel_hi:[1,0]
	v_pk_mul_f32 v[48:49], v[48:49], v[154:155] op_sel_hi:[1,0]
	v_pk_mul_f32 v[42:43], v[42:43], v[154:155] op_sel_hi:[1,0]
	v_pk_mul_f32 v[44:45], v[44:45], v[154:155] op_sel_hi:[1,0]
	v_pk_mul_f32 v[38:39], v[38:39], v[154:155] op_sel_hi:[1,0]
	v_pk_mul_f32 v[40:41], v[40:41], v[154:155] op_sel_hi:[1,0]
	v_pk_mul_f32 v[34:35], v[34:35], v[154:155] op_sel_hi:[1,0]
	v_pk_mul_f32 v[36:37], v[36:37], v[154:155] op_sel_hi:[1,0]
	v_add_f32_e32 v130, v203, v202
	v_add_f32_e32 v131, v204, v205
	v_add_u32_e32 v148, 0xb0, v156
	v_add_f32_e32 v130, v130, v131
	ds_bpermute_b32 v131, v221, v130
	v_ashrrev_i32_e32 v149, 31, v148
	s_waitcnt lgkmcnt(0)
	v_add_f32_e32 v130, v130, v131
	ds_bpermute_b32 v131, v222, v130
	s_waitcnt lgkmcnt(0)
	v_add_f32_e32 v130, v130, v131
	v_fmamk_f32 v130, v130, 0x3a800000, v231
	v_rsq_f32_e32 v150, v130
	s_nop 1
	v_pk_mul_f32 v[30:31], v[30:31], v[150:151] op_sel_hi:[1,0]
	v_pk_mul_f32 v[32:33], v[32:33], v[150:151] op_sel_hi:[1,0]
	v_pk_mul_f32 v[26:27], v[26:27], v[150:151] op_sel_hi:[1,0]
	v_pk_mul_f32 v[28:29], v[28:29], v[150:151] op_sel_hi:[1,0]
	v_pk_mul_f32 v[22:23], v[22:23], v[150:151] op_sel_hi:[1,0]
	v_pk_mul_f32 v[24:25], v[24:25], v[150:151] op_sel_hi:[1,0]
	v_pk_mul_f32 v[18:19], v[18:19], v[150:151] op_sel_hi:[1,0]
	v_pk_mul_f32 v[20:21], v[20:21], v[150:151] op_sel_hi:[1,0]
	v_add_f32_e32 v130, v207, v206
	v_add_f32_e32 v131, v208, v209
	v_mov_b64_e32 v[132:133], s[22:23]
	v_add_f32_e32 v130, v130, v131
	ds_bpermute_b32 v131, v221, v130
	v_mad_i64_i32 v[180:181], s[30:31], v156, s96, v[132:133]
	s_waitcnt lgkmcnt(0)
	v_add_f32_e32 v130, v130, v131
	ds_bpermute_b32 v131, v222, v130
	s_waitcnt lgkmcnt(0)
	v_add_f32_e32 v130, v130, v131
	v_lshl_or_b32 v131, s57, 8, v155
	v_ashrrev_i32_e32 v178, 1, v131
	v_mul_f32_e32 v131, 0xbfb8aa3b, v122
	v_exp_f32_e32 v131, v131
	v_ashrrev_i32_e32 v179, 31, v178
	v_lshlrev_b64 v[156:157], 1, v[178:179]
	v_lshl_add_u64 v[178:179], v[180:181], 0, v[156:157]
	v_add_f32_e32 v131, 1.0, v131
	v_rcp_f32_e32 v131, v131
	v_fmamk_f32 v130, v130, 0x3a800000, v231
	v_rsq_f32_e32 v130, v130
	v_mul_f32_e32 v122, v122, v131
	v_mul_f32_e32 v122, v123, v122
	v_mul_f32_e32 v123, 0xbfb8aa3b, v124
	v_exp_f32_e32 v123, v123
	v_pk_mul_f32 v[14:15], v[14:15], v[130:131] op_sel_hi:[1,0]
	v_pk_mul_f32 v[16:17], v[16:17], v[130:131] op_sel_hi:[1,0]
	v_pk_mul_f32 v[10:11], v[10:11], v[130:131] op_sel_hi:[1,0]
	v_add_f32_e32 v123, 1.0, v123
	v_rcp_f32_e32 v123, v123
	v_pk_mul_f32 v[12:13], v[12:13], v[130:131] op_sel_hi:[1,0]
	v_pk_mul_f32 v[6:7], v[6:7], v[130:131] op_sel_hi:[1,0]
	v_pk_mul_f32 v[8:9], v[8:9], v[130:131] op_sel_hi:[1,0]
	v_mul_f32_e32 v123, v124, v123
	v_mul_f32_e32 v123, v125, v123
	v_cvt_pk_bf16_f32 v122, v122, v123
	v_mul_f32_e32 v123, 0xbfb8aa3b, v126
	v_exp_f32_e32 v123, v123
	v_mul_f32_e32 v124, 0xbfb8aa3b, v128
	v_exp_f32_e32 v124, v124
	v_pk_mul_f32 v[2:3], v[2:3], v[130:131] op_sel_hi:[1,0]
	v_add_f32_e32 v123, 1.0, v123
	v_rcp_f32_e32 v123, v123
	v_add_f32_e32 v124, 1.0, v124
	v_rcp_f32_e32 v124, v124
	v_pk_mul_f32 v[4:5], v[4:5], v[130:131] op_sel_hi:[1,0]
	v_mul_f32_e32 v123, v126, v123
	v_mul_f32_e32 v123, v127, v123
	v_mul_f32_e32 v124, v128, v124
	v_mul_f32_e32 v124, v129, v124
	v_cvt_pk_bf16_f32 v123, v123, v124
	global_store_dwordx2 v[178:179], v[122:123], off
	v_mul_f32_e32 v122, 0xbfb8aa3b, v118
	v_exp_f32_e32 v122, v122
	s_nop 0
	v_add_f32_e32 v122, 1.0, v122
	v_rcp_f32_e32 v122, v122
	s_nop 0
	v_mul_f32_e32 v118, v118, v122
	v_mul_f32_e32 v118, v119, v118
	v_mul_f32_e32 v119, 0xbfb8aa3b, v120
	v_exp_f32_e32 v119, v119
	s_nop 0
	v_add_f32_e32 v119, 1.0, v119
	v_rcp_f32_e32 v119, v119
	s_nop 0
	v_mul_f32_e32 v119, v120, v119
	v_mul_f32_e32 v119, v121, v119
	v_cvt_pk_bf16_f32 v118, v118, v119
	v_mul_f32_e32 v119, 0xbfb8aa3b, v114
	v_exp_f32_e32 v119, v119
	s_nop 0
	v_add_f32_e32 v119, 1.0, v119
	v_rcp_f32_e32 v119, v119
	s_nop 0
	v_mul_f32_e32 v114, v114, v119
	v_mul_f32_e32 v114, v115, v114
	v_mul_f32_e32 v115, 0xbfb8aa3b, v116
	v_exp_f32_e32 v115, v115
	s_nop 0
	v_add_f32_e32 v115, 1.0, v115
	v_rcp_f32_e32 v115, v115
	s_nop 0
	v_mul_f32_e32 v115, v116, v115
	v_mul_f32_e32 v116, 0xbfb8aa3b, v110
	v_exp_f32_e32 v116, v116
	v_mul_f32_e32 v115, v117, v115
	v_cvt_pk_bf16_f32 v119, v114, v115
	global_store_dwordx2 v[178:179], v[118:119], off offset:128
	v_add_f32_e32 v116, 1.0, v116
	v_rcp_f32_e32 v116, v116
	v_mad_i64_i32 v[114:115], s[30:31], v174, s96, v[132:133]
	v_lshl_add_u64 v[114:115], v[114:115], 0, v[156:157]
	v_mul_f32_e32 v110, v110, v116
	v_mul_f32_e32 v110, v111, v110
	v_mul_f32_e32 v111, 0xbfb8aa3b, v112
	v_exp_f32_e32 v111, v111
	s_nop 0
	v_add_f32_e32 v111, 1.0, v111
	v_rcp_f32_e32 v111, v111
	s_nop 0
	v_mul_f32_e32 v111, v112, v111
	v_mul_f32_e32 v111, v113, v111
	v_cvt_pk_bf16_f32 v110, v110, v111
	v_mul_f32_e32 v111, 0xbfb8aa3b, v106
	v_exp_f32_e32 v111, v111
	s_nop 0
	v_add_f32_e32 v111, 1.0, v111
	v_rcp_f32_e32 v111, v111
	s_nop 0
	v_mul_f32_e32 v106, v106, v111
	v_mul_f32_e32 v106, v107, v106
	v_mul_f32_e32 v107, 0xbfb8aa3b, v108
	v_exp_f32_e32 v107, v107
	s_nop 0
	v_add_f32_e32 v107, 1.0, v107
	v_rcp_f32_e32 v107, v107
	s_nop 0
	v_mul_f32_e32 v107, v108, v107
	v_mul_f32_e32 v107, v109, v107
	v_cvt_pk_bf16_f32 v111, v106, v107
	v_mul_f32_e32 v106, 0xbfb8aa3b, v102
	v_exp_f32_e32 v106, v106
	global_store_dwordx2 v[114:115], v[110:111], off
	v_add_f32_e32 v106, 1.0, v106
	v_rcp_f32_e32 v106, v106
; __device__ __forceinline__ unsigned cvt_pk_bf16(float lo, float hi) { unsigned r; asm volatile("v_cvt_pk_bf16_f32 %0, %1, %2" : "=v"(r) : "v"(lo), "v"(hi)); return r; }
;     __device__ __forceinline__ static float sg(float g, float uu) { return g * __builtin_amdgcn_rcpf(1.0f + __builtin_amdgcn_exp2f(-1.4426950408889634f * g)) * uu; }
;     __device__ __forceinline__ void operator()(const f32x4 (&acc)[2][2][4][2], const Unit& u, int wr, int wc, int fr, int fq) const {
;         const int row0 = u.pm * BM + wr * 64 + fr, col0 = u.pn * BM + wc * 32 + 8 * fq;
;         float rsv[2][4];
; #pragma unroll
;         for (int ai = 0; ai < 2; ++ai) {
; #pragma unroll
;             for (int m = 0; m < 4; ++m) rsv[ai][m] = row_rstd16_coop(ssq, row0 + ai * HALF + m * 16, fq, 1.0f / 1024.0f);
;         }
; #pragma unroll
;         for (int ai = 0; ai < 2; ++ai)
; #pragma unroll
;             for (int m = 0; m < 4; ++m) {
;                 const int row = row0 + ai * HALF + m * 16;
;                 const float rs = rsv[ai][m];
;                 bf16_t* rowp = H + (size_t)row * ldh + (col0 >> 1);
; #pragma unroll
;                 for (int bj = 0; bj < 2; ++bj) {
;                     const f32x4 v0 = acc[ai][bj][m][0] * rs, v1 = acc[ai][bj][m][1] * rs;
;                     u32x2 w; w.x = cvt_pk_bf16(sg(v0[0], v0[1]), sg(v0[2], v0[3])); w.y = cvt_pk_bf16(sg(v1[0], v1[1]), sg(v1[2], v1[3]));
;                     *(u32x2*)(rowp + bj * (HALF / 2)) = w;
;                 }
	s_nop 0
	v_mul_f32_e32 v102, v102, v106
	v_mul_f32_e32 v102, v103, v102
	v_mul_f32_e32 v103, 0xbfb8aa3b, v104
	v_exp_f32_e32 v103, v103
	s_nop 0
	v_add_f32_e32 v103, 1.0, v103
	v_rcp_f32_e32 v103, v103
	s_nop 0
	v_mul_f32_e32 v103, v104, v103
	v_mul_f32_e32 v103, v105, v103
	v_cvt_pk_bf16_f32 v102, v102, v103
	v_mul_f32_e32 v103, 0xbfb8aa3b, v98
	v_exp_f32_e32 v103, v103
	s_nop 0
	v_add_f32_e32 v103, 1.0, v103
	v_rcp_f32_e32 v103, v103
	s_nop 0
	v_mul_f32_e32 v98, v98, v103
	v_mul_f32_e32 v98, v99, v98
	v_mul_f32_e32 v99, 0xbfb8aa3b, v100
	v_exp_f32_e32 v99, v99
	s_nop 0
	v_add_f32_e32 v99, 1.0, v99
	v_rcp_f32_e32 v99, v99
	s_nop 0
	v_mul_f32_e32 v99, v100, v99
	v_mul_f32_e32 v100, 0xbfb8aa3b, v94
	v_exp_f32_e32 v100, v100
	v_mul_f32_e32 v99, v101, v99
	v_cvt_pk_bf16_f32 v103, v98, v99
	global_store_dwordx2 v[114:115], v[102:103], off offset:128
	v_add_f32_e32 v100, 1.0, v100
	v_rcp_f32_e32 v100, v100
	v_mad_i64_i32 v[98:99], s[30:31], v170, s96, v[132:133]
	v_lshl_add_u64 v[98:99], v[98:99], 0, v[156:157]
	v_mul_f32_e32 v94, v94, v100
	v_mul_f32_e32 v94, v95, v94
	v_mul_f32_e32 v95, 0xbfb8aa3b, v96
	v_exp_f32_e32 v95, v95
	s_nop 0
	v_add_f32_e32 v95, 1.0, v95
	v_rcp_f32_e32 v95, v95
	s_nop 0
	v_mul_f32_e32 v95, v96, v95
	v_mul_f32_e32 v95, v97, v95
	v_cvt_pk_bf16_f32 v94, v94, v95
	v_mul_f32_e32 v95, 0xbfb8aa3b, v90
	v_exp_f32_e32 v95, v95
	s_nop 0
	v_add_f32_e32 v95, 1.0, v95
	v_rcp_f32_e32 v95, v95
	s_nop 0
	v_mul_f32_e32 v90, v90, v95
	v_mul_f32_e32 v90, v91, v90
	v_mul_f32_e32 v91, 0xbfb8aa3b, v92
	v_exp_f32_e32 v91, v91
	s_nop 0
	v_add_f32_e32 v91, 1.0, v91
	v_rcp_f32_e32 v91, v91
	s_nop 0
	v_mul_f32_e32 v91, v92, v91
	v_mul_f32_e32 v91, v93, v91
	v_cvt_pk_bf16_f32 v95, v90, v91
	v_mul_f32_e32 v90, 0xbfb8aa3b, v86
	v_exp_f32_e32 v90, v90
	global_store_dwordx2 v[98:99], v[94:95], off
	v_add_f32_e32 v90, 1.0, v90
	v_rcp_f32_e32 v90, v90
	s_nop 0
	v_mul_f32_e32 v86, v86, v90
	v_mul_f32_e32 v86, v87, v86
	v_mul_f32_e32 v87, 0xbfb8aa3b, v88
	v_exp_f32_e32 v87, v87
	s_nop 0
	v_add_f32_e32 v87, 1.0, v87
	v_rcp_f32_e32 v87, v87
	s_nop 0
	v_mul_f32_e32 v87, v88, v87
	v_mul_f32_e32 v87, v89, v87
	v_cvt_pk_bf16_f32 v86, v86, v87
	v_mul_f32_e32 v87, 0xbfb8aa3b, v82
	v_exp_f32_e32 v87, v87
	s_nop 0
	v_add_f32_e32 v87, 1.0, v87
	v_rcp_f32_e32 v87, v87
	s_nop 0
	v_mul_f32_e32 v82, v82, v87
	v_mul_f32_e32 v82, v83, v82
	v_mul_f32_e32 v83, 0xbfb8aa3b, v84
	v_exp_f32_e32 v83, v83
	s_nop 0
	v_add_f32_e32 v83, 1.0, v83
	v_rcp_f32_e32 v83, v83
	s_nop 0
	v_mul_f32_e32 v83, v84, v83
	v_mul_f32_e32 v84, 0xbfb8aa3b, v78
	v_exp_f32_e32 v84, v84
	v_mul_f32_e32 v83, v85, v83
	v_cvt_pk_bf16_f32 v87, v82, v83
	global_store_dwordx2 v[98:99], v[86:87], off offset:128
	v_add_f32_e32 v84, 1.0, v84
	v_rcp_f32_e32 v84, v84
	v_mad_i64_i32 v[82:83], s[30:31], v166, s96, v[132:133]
	v_lshl_add_u64 v[82:83], v[82:83], 0, v[156:157]
	v_mul_f32_e32 v78, v78, v84
	v_mul_f32_e32 v78, v79, v78
	v_mul_f32_e32 v79, 0xbfb8aa3b, v80
	v_exp_f32_e32 v79, v79
	s_nop 0
	v_add_f32_e32 v79, 1.0, v79
	v_rcp_f32_e32 v79, v79
	s_nop 0
	v_mul_f32_e32 v79, v80, v79
	v_mul_f32_e32 v79, v81, v79
	v_cvt_pk_bf16_f32 v78, v78, v79
	v_mul_f32_e32 v79, 0xbfb8aa3b, v74
	v_exp_f32_e32 v79, v79
	s_nop 0
	v_add_f32_e32 v79, 1.0, v79
	v_rcp_f32_e32 v79, v79
	s_nop 0
	v_mul_f32_e32 v74, v74, v79
	v_mul_f32_e32 v74, v75, v74
	v_mul_f32_e32 v75, 0xbfb8aa3b, v76
	v_exp_f32_e32 v75, v75
	s_nop 0
	v_add_f32_e32 v75, 1.0, v75
	v_rcp_f32_e32 v75, v75
	s_nop 0
	v_mul_f32_e32 v75, v76, v75
	v_mul_f32_e32 v75, v77, v75
	v_cvt_pk_bf16_f32 v79, v74, v75
	v_mul_f32_e32 v74, 0xbfb8aa3b, v70
	v_exp_f32_e32 v74, v74
	global_store_dwordx2 v[82:83], v[78:79], off
	v_add_f32_e32 v74, 1.0, v74
	v_rcp_f32_e32 v74, v74
	s_nop 0
	v_mul_f32_e32 v70, v70, v74
	v_mul_f32_e32 v70, v71, v70
	v_mul_f32_e32 v71, 0xbfb8aa3b, v72
	v_exp_f32_e32 v71, v71
	s_nop 0
	v_add_f32_e32 v71, 1.0, v71
	v_rcp_f32_e32 v71, v71
	s_nop 0
	v_mul_f32_e32 v71, v72, v71
	v_mul_f32_e32 v71, v73, v71
	v_cvt_pk_bf16_f32 v70, v70, v71
	v_mul_f32_e32 v71, 0xbfb8aa3b, v66
	v_exp_f32_e32 v71, v71
	s_nop 0
	v_add_f32_e32 v71, 1.0, v71
	v_rcp_f32_e32 v71, v71
	s_nop 0
	v_mul_f32_e32 v66, v66, v71
	v_mul_f32_e32 v66, v67, v66
	v_mul_f32_e32 v67, 0xbfb8aa3b, v68
	v_exp_f32_e32 v67, v67
	s_nop 0
	v_add_f32_e32 v67, 1.0, v67
	v_rcp_f32_e32 v67, v67
	s_nop 0
	v_mul_f32_e32 v67, v68, v67
	v_mul_f32_e32 v68, 0xbfb8aa3b, v62
	v_exp_f32_e32 v68, v68
	v_mul_f32_e32 v67, v69, v67
	v_cvt_pk_bf16_f32 v71, v66, v67
	global_store_dwordx2 v[82:83], v[70:71], off offset:128
	v_add_f32_e32 v68, 1.0, v68
	v_rcp_f32_e32 v68, v68
	v_mad_i64_i32 v[66:67], s[30:31], v162, s96, v[132:133]
	v_lshl_add_u64 v[66:67], v[66:67], 0, v[156:157]
	v_mul_f32_e32 v62, v62, v68
	v_mul_f32_e32 v62, v63, v62
	v_mul_f32_e32 v63, 0xbfb8aa3b, v64
	v_exp_f32_e32 v63, v63
	s_nop 0
	v_add_f32_e32 v63, 1.0, v63
	v_rcp_f32_e32 v63, v63
	s_nop 0
	v_mul_f32_e32 v63, v64, v63
	v_mul_f32_e32 v63, v65, v63
	v_cvt_pk_bf16_f32 v62, v62, v63
	v_mul_f32_e32 v63, 0xbfb8aa3b, v58
	v_exp_f32_e32 v63, v63
	s_nop 0
	v_add_f32_e32 v63, 1.0, v63
	v_rcp_f32_e32 v63, v63
	s_nop 0
	v_mul_f32_e32 v58, v58, v63
	v_mul_f32_e32 v58, v59, v58
	v_mul_f32_e32 v59, 0xbfb8aa3b, v60
	v_exp_f32_e32 v59, v59
	s_nop 0
	v_add_f32_e32 v59, 1.0, v59
	v_rcp_f32_e32 v59, v59
	s_nop 0
	v_mul_f32_e32 v59, v60, v59
	v_mul_f32_e32 v59, v61, v59
	v_cvt_pk_bf16_f32 v63, v58, v59
	v_mul_f32_e32 v58, 0xbfb8aa3b, v54
	v_exp_f32_e32 v58, v58
	global_store_dwordx2 v[66:67], v[62:63], off
	v_add_f32_e32 v58, 1.0, v58
	v_rcp_f32_e32 v58, v58
	s_nop 0
	v_mul_f32_e32 v54, v54, v58
	v_mul_f32_e32 v54, v55, v54
	v_mul_f32_e32 v55, 0xbfb8aa3b, v56
; __device__ __forceinline__ unsigned cvt_pk_bf16(float lo, float hi) { unsigned r; asm volatile("v_cvt_pk_bf16_f32 %0, %1, %2" : "=v"(r) : "v"(lo), "v"(hi)); return r; }
; #define PG8_BAR __builtin_amdgcn_s_barrier()
;     __device__ __forceinline__ static float sg(float g, float uu) { return g * __builtin_amdgcn_rcpf(1.0f + __builtin_amdgcn_exp2f(-1.4426950408889634f * g)) * uu; }
; template <class Epi, class Sched, bool ALIGN_EPI = false, bool SP2 = false>
; __device__ __forceinline__ void gemm_phase(PG8_LAS unsigned char* lds, const Gemm g, const Sched& S, const Epi& E) {
;     ...
;         if constexpr (ALIGN_EPI) { if (wr == 0) PG8_BAR; }
;         if constexpr (!Epi::AFTER_DRAIN) { E(acc, cur, wr, wc, fr, fq); S.done(cur); }
;         if (!has_next) break;
; #pragma unroll
;         for (int a = 0; a < 2; ++a)
; #pragma unroll
;             for (int b = 0; b < 2; ++b)
; #pragma unroll
;                 for (int m = 0; m < 4; ++m)
; #pragma unroll
;                     for (int n = 0; n < 2; ++n) acc[a][b][m][n] = (f32x4){0.f, 0.f, 0.f, 0.f};
;         cur = nxt; cA = nA; cB = nB; ++ui;
;         if constexpr (ALIGN_EPI) { if (wr == 1) PG8_BAR; }
;     __device__ __forceinline__ void operator()(const f32x4 (&acc)[2][2][4][2], const Unit& u, int wr, int wc, int fr, int fq) const {
;     ...
;         for (int ai = 0; ai < 2; ++ai)
; #pragma unroll
;             for (int m = 0; m < 4; ++m) {
;                 const int row = row0 + ai * HALF + m * 16;
;                 const float rs = rsv[ai][m];
;                 bf16_t* rowp = H + (size_t)row * ldh + (col0 >> 1);
; #pragma unroll
;                 for (int bj = 0; bj < 2; ++bj) {
;                     const f32x4 v0 = acc[ai][bj][m][0] * rs, v1 = acc[ai][bj][m][1] * rs;
;                     u32x2 w; w.x = cvt_pk_bf16(sg(v0[0], v0[1]), sg(v0[2], v0[3])); w.y = cvt_pk_bf16(sg(v1[0], v1[1]), sg(v1[2], v1[3]));
;                     *(u32x2*)(rowp + bj * (HALF / 2)) = w;
;                 }
;             }
	v_exp_f32_e32 v55, v55
	s_nop 0
	v_add_f32_e32 v55, 1.0, v55
	v_rcp_f32_e32 v55, v55
	s_nop 0
	v_mul_f32_e32 v55, v56, v55
	v_mul_f32_e32 v55, v57, v55
	v_cvt_pk_bf16_f32 v54, v54, v55
	v_mul_f32_e32 v55, 0xbfb8aa3b, v50
	v_exp_f32_e32 v55, v55
	s_nop 0
	v_add_f32_e32 v55, 1.0, v55
	v_rcp_f32_e32 v55, v55
	s_nop 0
	v_mul_f32_e32 v50, v50, v55
	v_mul_f32_e32 v50, v51, v50
	v_mul_f32_e32 v51, 0xbfb8aa3b, v52
	v_exp_f32_e32 v51, v51
	s_nop 0
	v_add_f32_e32 v51, 1.0, v51
	v_rcp_f32_e32 v51, v51
	s_nop 0
	v_mul_f32_e32 v51, v52, v51
	v_mul_f32_e32 v52, 0xbfb8aa3b, v46
	v_exp_f32_e32 v52, v52
	v_mul_f32_e32 v51, v53, v51
	v_cvt_pk_bf16_f32 v55, v50, v51
	global_store_dwordx2 v[66:67], v[54:55], off offset:128
	v_add_f32_e32 v52, 1.0, v52
	v_rcp_f32_e32 v52, v52
	v_mad_i64_i32 v[50:51], s[30:31], v158, s96, v[132:133]
	v_lshl_add_u64 v[50:51], v[50:51], 0, v[156:157]
	v_mul_f32_e32 v46, v46, v52
	v_mul_f32_e32 v46, v47, v46
	v_mul_f32_e32 v47, 0xbfb8aa3b, v48
	v_exp_f32_e32 v47, v47
	s_nop 0
	v_add_f32_e32 v47, 1.0, v47
	v_rcp_f32_e32 v47, v47
	s_nop 0
	v_mul_f32_e32 v47, v48, v47
	v_mul_f32_e32 v47, v49, v47
	v_cvt_pk_bf16_f32 v46, v46, v47
	v_mul_f32_e32 v47, 0xbfb8aa3b, v42
	v_exp_f32_e32 v47, v47
	s_nop 0
	v_add_f32_e32 v47, 1.0, v47
	v_rcp_f32_e32 v47, v47
	s_nop 0
	v_mul_f32_e32 v42, v42, v47
	v_mul_f32_e32 v42, v43, v42
	v_mul_f32_e32 v43, 0xbfb8aa3b, v44
	v_exp_f32_e32 v43, v43
	s_nop 0
	v_add_f32_e32 v43, 1.0, v43
	v_rcp_f32_e32 v43, v43
	s_nop 0
	v_mul_f32_e32 v43, v44, v43
	v_mul_f32_e32 v43, v45, v43
	v_cvt_pk_bf16_f32 v47, v42, v43
	v_mul_f32_e32 v42, 0xbfb8aa3b, v38
	v_exp_f32_e32 v42, v42
	global_store_dwordx2 v[50:51], v[46:47], off
	v_add_f32_e32 v42, 1.0, v42
	v_rcp_f32_e32 v42, v42
	s_nop 0
	v_mul_f32_e32 v38, v38, v42
	v_mul_f32_e32 v38, v39, v38
	v_mul_f32_e32 v39, 0xbfb8aa3b, v40
	v_exp_f32_e32 v39, v39
	s_nop 0
	v_add_f32_e32 v39, 1.0, v39
	v_rcp_f32_e32 v39, v39
	s_nop 0
	v_mul_f32_e32 v39, v40, v39
	v_mul_f32_e32 v39, v41, v39
	v_cvt_pk_bf16_f32 v38, v38, v39
	v_mul_f32_e32 v39, 0xbfb8aa3b, v34
	v_exp_f32_e32 v39, v39
	s_nop 0
	v_add_f32_e32 v39, 1.0, v39
	v_rcp_f32_e32 v39, v39
	s_nop 0
	v_mul_f32_e32 v34, v34, v39
	v_mul_f32_e32 v34, v35, v34
	v_mul_f32_e32 v35, 0xbfb8aa3b, v36
	v_exp_f32_e32 v35, v35
	s_nop 0
	v_add_f32_e32 v35, 1.0, v35
	v_rcp_f32_e32 v35, v35
	s_nop 0
	v_mul_f32_e32 v35, v36, v35
	v_mul_f32_e32 v36, 0xbfb8aa3b, v30
	v_exp_f32_e32 v36, v36
	v_mul_f32_e32 v35, v37, v35
	v_cvt_pk_bf16_f32 v39, v34, v35
	global_store_dwordx2 v[50:51], v[38:39], off offset:128
	v_add_f32_e32 v36, 1.0, v36
	v_rcp_f32_e32 v36, v36
	v_mad_i64_i32 v[34:35], s[30:31], v152, s96, v[132:133]
	v_lshl_add_u64 v[34:35], v[34:35], 0, v[156:157]
	v_mul_f32_e32 v30, v30, v36
	v_mul_f32_e32 v30, v31, v30
	v_mul_f32_e32 v31, 0xbfb8aa3b, v32
	v_exp_f32_e32 v31, v31
	s_nop 0
	v_add_f32_e32 v31, 1.0, v31
	v_rcp_f32_e32 v31, v31
	s_nop 0
	v_mul_f32_e32 v31, v32, v31
	v_mul_f32_e32 v31, v33, v31
	v_cvt_pk_bf16_f32 v30, v30, v31
	v_mul_f32_e32 v31, 0xbfb8aa3b, v26
	v_exp_f32_e32 v31, v31
	s_nop 0
	v_add_f32_e32 v31, 1.0, v31
	v_rcp_f32_e32 v31, v31
	s_nop 0
	v_mul_f32_e32 v26, v26, v31
	v_mul_f32_e32 v26, v27, v26
	v_mul_f32_e32 v27, 0xbfb8aa3b, v28
	v_exp_f32_e32 v27, v27
	s_nop 0
	v_add_f32_e32 v27, 1.0, v27
	v_rcp_f32_e32 v27, v27
	s_nop 0
	v_mul_f32_e32 v27, v28, v27
	v_mul_f32_e32 v27, v29, v27
	v_cvt_pk_bf16_f32 v31, v26, v27
	v_mul_f32_e32 v26, 0xbfb8aa3b, v22
	v_exp_f32_e32 v26, v26
	global_store_dwordx2 v[34:35], v[30:31], off
	v_add_f32_e32 v26, 1.0, v26
	v_rcp_f32_e32 v26, v26
	s_nop 0
	v_mul_f32_e32 v22, v22, v26
	v_mul_f32_e32 v22, v23, v22
	v_mul_f32_e32 v23, 0xbfb8aa3b, v24
	v_exp_f32_e32 v23, v23
	s_nop 0
	v_add_f32_e32 v23, 1.0, v23
	v_rcp_f32_e32 v23, v23
	s_nop 0
	v_mul_f32_e32 v23, v24, v23
	v_mul_f32_e32 v23, v25, v23
	v_cvt_pk_bf16_f32 v22, v22, v23
	v_mul_f32_e32 v23, 0xbfb8aa3b, v18
	v_exp_f32_e32 v23, v23
	s_nop 0
	v_add_f32_e32 v23, 1.0, v23
	v_rcp_f32_e32 v23, v23
	s_nop 0
	v_mul_f32_e32 v18, v18, v23
	v_mul_f32_e32 v18, v19, v18
	v_mul_f32_e32 v19, 0xbfb8aa3b, v20
	v_exp_f32_e32 v19, v19
	s_nop 0
	v_add_f32_e32 v19, 1.0, v19
	v_rcp_f32_e32 v19, v19
	s_nop 0
	v_mul_f32_e32 v19, v20, v19
	v_mul_f32_e32 v20, 0xbfb8aa3b, v14
	v_exp_f32_e32 v20, v20
	v_mul_f32_e32 v19, v21, v19
	v_cvt_pk_bf16_f32 v23, v18, v19
	global_store_dwordx2 v[34:35], v[22:23], off offset:128
	v_add_f32_e32 v20, 1.0, v20
	v_rcp_f32_e32 v20, v20
	v_mad_i64_i32 v[18:19], s[30:31], v148, s96, v[132:133]
	v_lshl_add_u64 v[18:19], v[18:19], 0, v[156:157]
	v_mul_f32_e32 v14, v14, v20
	v_mul_f32_e32 v14, v15, v14
	v_mul_f32_e32 v15, 0xbfb8aa3b, v16
	v_exp_f32_e32 v15, v15
	s_mov_b64 s[30:31], -1
	v_add_f32_e32 v15, 1.0, v15
	v_rcp_f32_e32 v15, v15
	s_nop 0
	v_mul_f32_e32 v15, v16, v15
	v_mul_f32_e32 v15, v17, v15
	v_cvt_pk_bf16_f32 v14, v14, v15
	v_mul_f32_e32 v15, 0xbfb8aa3b, v10
	v_exp_f32_e32 v15, v15
	s_nop 0
	v_add_f32_e32 v15, 1.0, v15
	v_rcp_f32_e32 v15, v15
	s_nop 0
	v_mul_f32_e32 v10, v10, v15
	v_mul_f32_e32 v10, v11, v10
	v_mul_f32_e32 v11, 0xbfb8aa3b, v12
	v_exp_f32_e32 v11, v11
	s_nop 0
	v_add_f32_e32 v11, 1.0, v11
	v_rcp_f32_e32 v11, v11
	s_nop 0
	v_mul_f32_e32 v11, v12, v11
	v_mul_f32_e32 v11, v13, v11
	v_cvt_pk_bf16_f32 v15, v10, v11
	v_mul_f32_e32 v10, 0xbfb8aa3b, v6
	v_exp_f32_e32 v10, v10
	global_store_dwordx2 v[18:19], v[14:15], off
	v_add_f32_e32 v10, 1.0, v10
	v_rcp_f32_e32 v10, v10
	s_nop 0
	v_mul_f32_e32 v6, v6, v10
	v_mul_f32_e32 v6, v7, v6
	v_mul_f32_e32 v7, 0xbfb8aa3b, v8
	v_exp_f32_e32 v7, v7
	s_nop 0
	v_add_f32_e32 v7, 1.0, v7
	v_rcp_f32_e32 v7, v7
	s_nop 0
	v_mul_f32_e32 v7, v8, v7
	v_mul_f32_e32 v7, v9, v7
	v_cvt_pk_bf16_f32 v6, v6, v7
	v_mul_f32_e32 v7, 0xbfb8aa3b, v2
	v_exp_f32_e32 v7, v7
	s_nop 0
	v_add_f32_e32 v7, 1.0, v7
	v_rcp_f32_e32 v7, v7
	s_nop 0
	v_mul_f32_e32 v2, v2, v7
	v_mul_f32_e32 v2, v3, v2
	v_mul_f32_e32 v3, 0xbfb8aa3b, v4
	v_exp_f32_e32 v3, v3
	s_nop 0
	v_add_f32_e32 v3, 1.0, v3
	v_rcp_f32_e32 v3, v3
	s_nop 0
	v_mul_f32_e32 v3, v4, v3
	v_mul_f32_e32 v3, v5, v3
	v_cvt_pk_bf16_f32 v7, v2, v3
	global_store_dwordx2 v[18:19], v[6:7], off offset:128
	s_cbranch_vccnz .LBB0_3152
	s_andn2_b64 vcc, exec, s[20:21]
	s_cbranch_vccnz .LBB0_3151
	s_barrier
	s_branch .LBB0_3151

; __device__ __forceinline__ unsigned cvt_pk_bf16(float lo, float hi) { unsigned r; asm volatile("v_cvt_pk_bf16_f32 %0, %1, %2" : "=v"(r) : "v"(lo), "v"(hi)); return r; }
; __device__ __forceinline__ float row_rstd16_coop(const float* ssq, int row, int fq, float inv_n) {
;     const f32x4 a = *(const f32x4*)(ssq + (size_t)row * 16 + fq * 4);
;     float s = (a[0] + a[1]) + (a[2] + a[3]);
;     s += __shfl_xor(s, 16); s += __shfl_xor(s, 32);
;     return __builtin_amdgcn_rsqf(s * inv_n + EPS);
;     __device__ __forceinline__ void operator()(const f32x4 (&acc)[2][2][4][2], const Unit& u, int wr, int wc, int fr, int fq) const {
;         const int row0 = u.pm * BM + wr * 64 + fr, col0 = u.pn * BM + wc * 32 + 8 * fq;
;         float rsv[2][4];
; #pragma unroll
;         for (int ai = 0; ai < 2; ++ai) {
; #pragma unroll
;             for (int m = 0; m < 4; ++m) rsv[ai][m] = ssq ? row_rstd16_coop(ssq, row0 + ai * HALF + m * 16, fq, 1.0f / 1024.0f) : 1.0f;
;         }
; #pragma unroll
;         for (int ai = 0; ai < 2; ++ai)
; #pragma unroll
;             for (int m = 0; m < 4; ++m) {
;                 const int row = row0 + ai * HALF + m * 16;
;                 const float rs = rsv[ai][m];
;                 bf16_t* rowp = O + (size_t)row * ldc + col0;
; #pragma unroll
;                 for (int bj = 0; bj < 2; ++bj) {
;                     const f32x4 v0 = acc[ai][bj][m][0] * rs, v1 = acc[ai][bj][m][1] * rs;
;                     u32x4 w; w.x = cvt_pk_bf16(v0[0], v0[1]); w.y = cvt_pk_bf16(v0[2], v0[3]); w.z = cvt_pk_bf16(v1[0], v1[1]); w.w = cvt_pk_bf16(v1[2], v1[3]);
;                     *(u32x4*)(rowp + bj * HALF) = w;
.LBB0_3349:
	v_lshl_add_u32 v162, s55, 8, v1
	v_ashrrev_i32_e32 v163, 31, v162
	v_lshlrev_b64 v[130:131], 6, v[162:163]
	v_lshl_add_u64 v[130:131], v[142:143], 0, v[130:131]
	global_load_dwordx4 v[180:183], v[130:131], off offset:1024
	global_load_dwordx4 v[184:187], v[130:131], off offset:2048
	global_load_dwordx4 v[188:191], v[130:131], off offset:3072
	v_add_co_u32_e32 v208, vcc, 0x2000, v130
	s_nop 1
	v_addc_co_u32_e32 v209, vcc, 0, v131, vcc
	global_load_dwordx4 v[192:195], v[208:209], off
	global_load_dwordx4 v[196:199], v[208:209], off offset:1024
	global_load_dwordx4 v[200:203], v[208:209], off offset:2048
	global_load_dwordx4 v[204:207], v[208:209], off offset:3072
	global_load_dwordx4 v[130:133], v[130:131], off
	v_or_b32_e32 v164, 16, v162
	v_ashrrev_i32_e32 v165, 31, v164
	v_or_b32_e32 v166, 32, v162
	v_ashrrev_i32_e32 v167, 31, v166
	v_or_b32_e32 v168, 48, v162
	v_ashrrev_i32_e32 v169, 31, v168
	v_add_u32_e32 v170, 0x80, v162
	v_ashrrev_i32_e32 v171, 31, v170
	v_add_u32_e32 v172, 0x90, v162
	v_ashrrev_i32_e32 v173, 31, v172
	v_add_u32_e32 v174, 0xa0, v162
	v_ashrrev_i32_e32 v175, 31, v174
	v_add_u32_e32 v176, 0xb0, v162
	v_ashrrev_i32_e32 v177, 31, v176
	v_mad_i64_i32 v[162:163], s[26:27], v162, s30, 0
	v_lshl_add_u64 v[162:163], v[162:163], 1, s[18:19]
	s_and_b64 vcc, exec, s[4:5]
	s_waitcnt vmcnt(0)
	v_mov_b32_e32 v154, v131
	v_mov_b32_e32 v155, v132
	v_mov_b32_e32 v131, v133
	v_pk_add_f32 v[130:131], v[154:155], v[130:131]
	s_nop 0
	v_add_f32_e32 v130, v130, v131
	ds_bpermute_b32 v131, v221, v130
	s_waitcnt lgkmcnt(0)
	v_add_f32_e32 v130, v130, v131
	ds_bpermute_b32 v131, v222, v130
	s_waitcnt lgkmcnt(0)
	v_add_f32_e32 v130, v130, v131
	v_fmamk_f32 v130, v130, 0x3a800000, v231
	v_rsq_f32_e32 v148, v130
	s_nop 1
	v_pk_mul_f32 v[128:129], v[128:129], v[148:149] op_sel_hi:[1,0]
	v_pk_mul_f32 v[126:127], v[126:127], v[148:149] op_sel_hi:[1,0]
	v_pk_mul_f32 v[120:121], v[120:121], v[148:149] op_sel_hi:[1,0]
	v_pk_mul_f32 v[118:119], v[118:119], v[148:149] op_sel_hi:[1,0]
	v_add_f32_e32 v130, v181, v180
	v_add_f32_e32 v131, v182, v183
	s_nop 0
	v_add_f32_e32 v130, v130, v131
	ds_bpermute_b32 v131, v221, v130
	s_waitcnt lgkmcnt(0)
	v_add_f32_e32 v130, v130, v131
	ds_bpermute_b32 v131, v222, v130
	s_waitcnt lgkmcnt(0)
	v_add_f32_e32 v130, v130, v131
	v_fmamk_f32 v130, v130, 0x3a800000, v231
	v_rsq_f32_e32 v150, v130
	s_nop 1
	v_pk_mul_f32 v[112:113], v[112:113], v[150:151] op_sel_hi:[1,0]
	v_pk_mul_f32 v[110:111], v[110:111], v[150:151] op_sel_hi:[1,0]
	v_pk_mul_f32 v[104:105], v[104:105], v[150:151] op_sel_hi:[1,0]
	v_pk_mul_f32 v[102:103], v[102:103], v[150:151] op_sel_hi:[1,0]
	v_add_f32_e32 v130, v185, v184
	v_add_f32_e32 v131, v186, v187
	s_nop 0
	v_add_f32_e32 v130, v130, v131
	ds_bpermute_b32 v131, v221, v130
	s_waitcnt lgkmcnt(0)
	v_add_f32_e32 v130, v130, v131
	ds_bpermute_b32 v131, v222, v130
	s_waitcnt lgkmcnt(0)
	v_add_f32_e32 v130, v130, v131
	v_fmamk_f32 v130, v130, 0x3a800000, v231
	v_rsq_f32_e32 v152, v130
	s_nop 1
	v_pk_mul_f32 v[96:97], v[96:97], v[152:153] op_sel_hi:[1,0]
	v_pk_mul_f32 v[94:95], v[94:95], v[152:153] op_sel_hi:[1,0]
	v_pk_mul_f32 v[88:89], v[88:89], v[152:153] op_sel_hi:[1,0]
	v_pk_mul_f32 v[86:87], v[86:87], v[152:153] op_sel_hi:[1,0]
	v_add_f32_e32 v130, v189, v188
	v_add_f32_e32 v131, v190, v191
	s_nop 0
	v_add_f32_e32 v130, v130, v131
	ds_bpermute_b32 v131, v221, v130
	s_waitcnt lgkmcnt(0)
	v_add_f32_e32 v130, v130, v131
	ds_bpermute_b32 v131, v222, v130
	s_waitcnt lgkmcnt(0)
	v_add_f32_e32 v130, v130, v131
	v_fmamk_f32 v130, v130, 0x3a800000, v231
	v_rsq_f32_e32 v154, v130
	s_nop 1
	v_pk_mul_f32 v[80:81], v[80:81], v[154:155] op_sel_hi:[1,0]
	v_pk_mul_f32 v[78:79], v[78:79], v[154:155] op_sel_hi:[1,0]
	v_pk_mul_f32 v[72:73], v[72:73], v[154:155] op_sel_hi:[1,0]
	v_pk_mul_f32 v[70:71], v[70:71], v[154:155] op_sel_hi:[1,0]
	v_add_f32_e32 v130, v193, v192
	v_add_f32_e32 v131, v194, v195
	s_nop 0
	v_add_f32_e32 v130, v130, v131
	ds_bpermute_b32 v131, v221, v130
	s_waitcnt lgkmcnt(0)
	v_add_f32_e32 v130, v130, v131
	ds_bpermute_b32 v131, v222, v130
	s_waitcnt lgkmcnt(0)
	v_add_f32_e32 v130, v130, v131
	v_fmamk_f32 v130, v130, 0x3a800000, v231
	v_rsq_f32_e32 v156, v130
	s_nop 1
	v_pk_mul_f32 v[64:65], v[64:65], v[156:157] op_sel_hi:[1,0]
	v_pk_mul_f32 v[62:63], v[62:63], v[156:157] op_sel_hi:[1,0]
	v_pk_mul_f32 v[56:57], v[56:57], v[156:157] op_sel_hi:[1,0]
	v_pk_mul_f32 v[54:55], v[54:55], v[156:157] op_sel_hi:[1,0]
	v_add_f32_e32 v130, v197, v196
	v_add_f32_e32 v131, v198, v199
	s_nop 0
	v_add_f32_e32 v130, v130, v131
	ds_bpermute_b32 v131, v221, v130
	s_waitcnt lgkmcnt(0)
	v_add_f32_e32 v130, v130, v131
	ds_bpermute_b32 v131, v222, v130
	s_waitcnt lgkmcnt(0)
	v_add_f32_e32 v130, v130, v131
	v_fmamk_f32 v130, v130, 0x3a800000, v231
	v_rsq_f32_e32 v158, v130
	s_nop 1
	v_pk_mul_f32 v[48:49], v[48:49], v[158:159] op_sel_hi:[1,0]
	v_pk_mul_f32 v[46:47], v[46:47], v[158:159] op_sel_hi:[1,0]
	v_pk_mul_f32 v[40:41], v[40:41], v[158:159] op_sel_hi:[1,0]
	v_pk_mul_f32 v[38:39], v[38:39], v[158:159] op_sel_hi:[1,0]
	v_add_f32_e32 v130, v201, v200
	v_add_f32_e32 v131, v202, v203
	s_nop 0
	v_add_f32_e32 v130, v130, v131
	ds_bpermute_b32 v131, v221, v130
	s_waitcnt lgkmcnt(0)
	v_add_f32_e32 v130, v130, v131
	ds_bpermute_b32 v131, v222, v130
	s_waitcnt lgkmcnt(0)
	v_add_f32_e32 v130, v130, v131
	v_fmamk_f32 v130, v130, 0x3a800000, v231
	v_rsq_f32_e32 v160, v130
	s_nop 1
	v_mov_b32_e32 v130, v204
	v_mov_b32_e32 v131, v205
	v_mov_b32_e32 v132, v206
	v_mov_b32_e32 v133, v207
	v_pk_mul_f32 v[32:33], v[32:33], v[160:161] op_sel_hi:[1,0]
	v_pk_mul_f32 v[30:31], v[30:31], v[160:161] op_sel_hi:[1,0]
	v_pk_mul_f32 v[24:25], v[24:25], v[160:161] op_sel_hi:[1,0]
	v_pk_mul_f32 v[22:23], v[22:23], v[160:161] op_sel_hi:[1,0]
	s_waitcnt vmcnt(0)
; __device__ __forceinline__ unsigned cvt_pk_bf16(float lo, float hi) { unsigned r; asm volatile("v_cvt_pk_bf16_f32 %0, %1, %2" : "=v"(r) : "v"(lo), "v"(hi)); return r; }
;     __device__ __forceinline__ void operator()(const f32x4 (&acc)[2][2][4][2], const Unit& u, int wr, int wc, int fr, int fq) const {
;         const int row0 = u.pm * BM + wr * 64 + fr, col0 = u.pn * BM + wc * 32 + 8 * fq;
;         float rsv[2][4];
; #pragma unroll
;         for (int ai = 0; ai < 2; ++ai) {
; #pragma unroll
;             for (int m = 0; m < 4; ++m) rsv[ai][m] = ssq ? row_rstd16_coop(ssq, row0 + ai * HALF + m * 16, fq, 1.0f / 1024.0f) : 1.0f;
;         }
; #pragma unroll
;         for (int ai = 0; ai < 2; ++ai)
; #pragma unroll
;             for (int m = 0; m < 4; ++m) {
;                 const int row = row0 + ai * HALF + m * 16;
;                 const float rs = rsv[ai][m];
;                 bf16_t* rowp = O + (size_t)row * ldc + col0;
; #pragma unroll
;                 for (int bj = 0; bj < 2; ++bj) {
;                     const f32x4 v0 = acc[ai][bj][m][0] * rs, v1 = acc[ai][bj][m][1] * rs;
;                     u32x4 w; w.x = cvt_pk_bf16(v0[0], v0[1]); w.y = cvt_pk_bf16(v0[2], v0[3]); w.z = cvt_pk_bf16(v1[0], v1[1]); w.w = cvt_pk_bf16(v1[2], v1[3]);
;                     *(u32x4*)(rowp + bj * HALF) = w;
;                 }
;             }
	v_mov_b32_e32 v179, v132
	v_lshl_or_b32 v132, s54, 8, v151
	v_mov_b32_e32 v178, v131
	v_mov_b32_e32 v131, v133
	v_ashrrev_i32_e32 v133, 31, v132
	v_lshlrev_b64 v[132:133], 1, v[132:133]
	v_pk_add_f32 v[130:131], v[178:179], v[130:131]
	v_lshl_add_u64 v[162:163], v[162:163], 0, v[132:133]
	v_pk_mul_f32 v[178:179], v[124:125], v[148:149] op_sel_hi:[1,0]
	v_pk_mul_f32 v[124:125], v[122:123], v[148:149] op_sel_hi:[1,0]
	v_cvt_pk_bf16_f32 v122, v126, v127
	v_cvt_pk_bf16_f32 v123, v128, v129
	v_add_f32_e32 v130, v130, v131
	v_cvt_pk_bf16_f32 v124, v124, v125
	v_cvt_pk_bf16_f32 v125, v178, v179
	global_store_dwordx4 v[162:163], v[122:125], off
	ds_bpermute_b32 v131, v221, v130
	s_waitcnt lgkmcnt(0)
	v_add_f32_e32 v130, v130, v131
	v_pk_mul_f32 v[122:123], v[116:117], v[148:149] op_sel_hi:[1,0]
	v_pk_mul_f32 v[116:117], v[114:115], v[148:149] op_sel_hi:[1,0]
	v_cvt_pk_bf16_f32 v114, v118, v119
	v_cvt_pk_bf16_f32 v115, v120, v121
	ds_bpermute_b32 v131, v222, v130
	v_cvt_pk_bf16_f32 v116, v116, v117
	v_cvt_pk_bf16_f32 v117, v122, v123
	global_store_dwordx4 v[162:163], v[114:117], off offset:256
	s_waitcnt lgkmcnt(0)
	v_add_f32_e32 v130, v130, v131
	v_mad_i64_i32 v[114:115], s[26:27], v164, s30, 0
	v_lshl_add_u64 v[114:115], v[114:115], 1, s[18:19]
	v_lshl_add_u64 v[114:115], v[114:115], 0, v[132:133]
	v_pk_mul_f32 v[116:117], v[108:109], v[150:151] op_sel_hi:[1,0]
	v_pk_mul_f32 v[108:109], v[106:107], v[150:151] op_sel_hi:[1,0]
	v_cvt_pk_bf16_f32 v106, v110, v111
	v_cvt_pk_bf16_f32 v107, v112, v113
	v_fmamk_f32 v130, v130, 0x3a800000, v231
	v_cvt_pk_bf16_f32 v108, v108, v109
	v_cvt_pk_bf16_f32 v109, v116, v117
	global_store_dwordx4 v[114:115], v[106:109], off
	v_rsq_f32_e32 v130, v130
	s_nop 0
	v_pk_mul_f32 v[106:107], v[100:101], v[150:151] op_sel_hi:[1,0]
	v_pk_mul_f32 v[100:101], v[98:99], v[150:151] op_sel_hi:[1,0]
	v_cvt_pk_bf16_f32 v98, v102, v103
	v_cvt_pk_bf16_f32 v99, v104, v105
	v_pk_mul_f32 v[16:17], v[16:17], v[130:131] op_sel_hi:[1,0]
	v_cvt_pk_bf16_f32 v100, v100, v101
	v_cvt_pk_bf16_f32 v101, v106, v107
	global_store_dwordx4 v[114:115], v[98:101], off offset:256
	v_pk_mul_f32 v[14:15], v[14:15], v[130:131] op_sel_hi:[1,0]
	v_pk_mul_f32 v[8:9], v[8:9], v[130:131] op_sel_hi:[1,0]
	v_mad_i64_i32 v[98:99], s[26:27], v166, s30, 0
	v_lshl_add_u64 v[98:99], v[98:99], 1, s[18:19]
	v_lshl_add_u64 v[98:99], v[98:99], 0, v[132:133]
	v_pk_mul_f32 v[100:101], v[92:93], v[152:153] op_sel_hi:[1,0]
	v_pk_mul_f32 v[92:93], v[90:91], v[152:153] op_sel_hi:[1,0]
	v_cvt_pk_bf16_f32 v90, v94, v95
	v_cvt_pk_bf16_f32 v91, v96, v97
	v_pk_mul_f32 v[6:7], v[6:7], v[130:131] op_sel_hi:[1,0]
	v_cvt_pk_bf16_f32 v92, v92, v93
	v_cvt_pk_bf16_f32 v93, v100, v101
	global_store_dwordx4 v[98:99], v[90:93], off
	s_nop 1
	v_pk_mul_f32 v[90:91], v[84:85], v[152:153] op_sel_hi:[1,0]
	v_pk_mul_f32 v[84:85], v[82:83], v[152:153] op_sel_hi:[1,0]
	v_cvt_pk_bf16_f32 v82, v86, v87
	v_cvt_pk_bf16_f32 v83, v88, v89
	s_nop 0
	v_cvt_pk_bf16_f32 v84, v84, v85
	v_cvt_pk_bf16_f32 v85, v90, v91
	global_store_dwordx4 v[98:99], v[82:85], off offset:256
	s_nop 1
	v_mad_i64_i32 v[82:83], s[26:27], v168, s30, 0
	v_lshl_add_u64 v[82:83], v[82:83], 1, s[18:19]
	v_lshl_add_u64 v[82:83], v[82:83], 0, v[132:133]
	v_pk_mul_f32 v[84:85], v[76:77], v[154:155] op_sel_hi:[1,0]
	v_pk_mul_f32 v[76:77], v[74:75], v[154:155] op_sel_hi:[1,0]
	v_cvt_pk_bf16_f32 v74, v78, v79
	v_cvt_pk_bf16_f32 v75, v80, v81
	s_nop 0
	v_cvt_pk_bf16_f32 v76, v76, v77
	v_cvt_pk_bf16_f32 v77, v84, v85
	global_store_dwordx4 v[82:83], v[74:77], off
	s_nop 1
	v_pk_mul_f32 v[74:75], v[68:69], v[154:155] op_sel_hi:[1,0]
	v_pk_mul_f32 v[68:69], v[66:67], v[154:155] op_sel_hi:[1,0]
	v_cvt_pk_bf16_f32 v66, v70, v71
	v_cvt_pk_bf16_f32 v67, v72, v73
	s_nop 0
	v_cvt_pk_bf16_f32 v68, v68, v69
	v_cvt_pk_bf16_f32 v69, v74, v75
	global_store_dwordx4 v[82:83], v[66:69], off offset:256
	s_nop 1
	v_mad_i64_i32 v[66:67], s[26:27], v170, s30, 0
	v_lshl_add_u64 v[66:67], v[66:67], 1, s[18:19]
	v_lshl_add_u64 v[66:67], v[66:67], 0, v[132:133]
	v_pk_mul_f32 v[68:69], v[60:61], v[156:157] op_sel_hi:[1,0]
	v_pk_mul_f32 v[60:61], v[58:59], v[156:157] op_sel_hi:[1,0]
	v_cvt_pk_bf16_f32 v58, v62, v63
	v_cvt_pk_bf16_f32 v59, v64, v65
	s_nop 0
	v_cvt_pk_bf16_f32 v60, v60, v61
	v_cvt_pk_bf16_f32 v61, v68, v69
	global_store_dwordx4 v[66:67], v[58:61], off
	s_nop 1
	v_pk_mul_f32 v[58:59], v[52:53], v[156:157] op_sel_hi:[1,0]
	v_pk_mul_f32 v[52:53], v[50:51], v[156:157] op_sel_hi:[1,0]
	v_cvt_pk_bf16_f32 v50, v54, v55
	v_cvt_pk_bf16_f32 v51, v56, v57
	s_nop 0
	v_cvt_pk_bf16_f32 v52, v52, v53
	v_cvt_pk_bf16_f32 v53, v58, v59
	global_store_dwordx4 v[66:67], v[50:53], off offset:256
	s_nop 1
	v_mad_i64_i32 v[50:51], s[26:27], v172, s30, 0
	v_lshl_add_u64 v[50:51], v[50:51], 1, s[18:19]
	v_lshl_add_u64 v[50:51], v[50:51], 0, v[132:133]
	v_pk_mul_f32 v[52:53], v[44:45], v[158:159] op_sel_hi:[1,0]
	v_pk_mul_f32 v[44:45], v[42:43], v[158:159] op_sel_hi:[1,0]
	v_cvt_pk_bf16_f32 v42, v46, v47
	v_cvt_pk_bf16_f32 v43, v48, v49
	s_nop 0
	v_cvt_pk_bf16_f32 v44, v44, v45
	v_cvt_pk_bf16_f32 v45, v52, v53
	global_store_dwordx4 v[50:51], v[42:45], off
	s_nop 1
	v_pk_mul_f32 v[42:43], v[36:37], v[158:159] op_sel_hi:[1,0]
	v_pk_mul_f32 v[36:37], v[34:35], v[158:159] op_sel_hi:[1,0]
	v_cvt_pk_bf16_f32 v34, v38, v39
	v_cvt_pk_bf16_f32 v35, v40, v41
	s_nop 0
	v_cvt_pk_bf16_f32 v36, v36, v37
	v_cvt_pk_bf16_f32 v37, v42, v43
	global_store_dwordx4 v[50:51], v[34:37], off offset:256
	s_nop 1
	v_mad_i64_i32 v[34:35], s[26:27], v174, s30, 0
	v_lshl_add_u64 v[34:35], v[34:35], 1, s[18:19]
	v_lshl_add_u64 v[34:35], v[34:35], 0, v[132:133]
	v_pk_mul_f32 v[36:37], v[28:29], v[160:161] op_sel_hi:[1,0]
	v_pk_mul_f32 v[28:29], v[26:27], v[160:161] op_sel_hi:[1,0]
	v_cvt_pk_bf16_f32 v26, v30, v31
	v_cvt_pk_bf16_f32 v27, v32, v33
	s_nop 0
	v_cvt_pk_bf16_f32 v28, v28, v29
	v_cvt_pk_bf16_f32 v29, v36, v37
	global_store_dwordx4 v[34:35], v[26:29], off
	s_nop 1
	v_pk_mul_f32 v[26:27], v[20:21], v[160:161] op_sel_hi:[1,0]
	v_pk_mul_f32 v[20:21], v[18:19], v[160:161] op_sel_hi:[1,0]
	v_cvt_pk_bf16_f32 v18, v22, v23
	v_cvt_pk_bf16_f32 v19, v24, v25
	s_nop 0
	v_cvt_pk_bf16_f32 v20, v20, v21
	v_cvt_pk_bf16_f32 v21, v26, v27
	global_store_dwordx4 v[34:35], v[18:21], off offset:256
	s_nop 1
	v_mad_i64_i32 v[18:19], s[26:27], v176, s30, 0
	v_lshl_add_u64 v[18:19], v[18:19], 1, s[18:19]
	v_lshl_add_u64 v[18:19], v[18:19], 0, v[132:133]
	v_pk_mul_f32 v[20:21], v[12:13], v[130:131] op_sel_hi:[1,0]
	v_pk_mul_f32 v[12:13], v[10:11], v[130:131] op_sel_hi:[1,0]
	v_cvt_pk_bf16_f32 v10, v14, v15
	v_cvt_pk_bf16_f32 v11, v16, v17
	s_mov_b64 s[26:27], -1
	v_cvt_pk_bf16_f32 v12, v12, v13
	v_cvt_pk_bf16_f32 v13, v20, v21
	global_store_dwordx4 v[18:19], v[10:13], off
	s_nop 1
	v_pk_mul_f32 v[10:11], v[4:5], v[130:131] op_sel_hi:[1,0]
	v_pk_mul_f32 v[4:5], v[2:3], v[130:131] op_sel_hi:[1,0]
	v_cvt_pk_bf16_f32 v2, v6, v7
	v_cvt_pk_bf16_f32 v3, v8, v9
	s_nop 0
	v_cvt_pk_bf16_f32 v4, v4, v5
	v_cvt_pk_bf16_f32 v5, v10, v11
	global_store_dwordx4 v[18:19], v[2:5], off offset:256
	s_cbranch_vccnz .LBB0_3333
; #define PG8_BAR __builtin_amdgcn_s_barrier()
; template <class Epi, class Sched, bool ALIGN_EPI = false, bool SP2 = false>
; __device__ __forceinline__ void gemm_phase(PG8_LAS unsigned char* lds, const Gemm g, const Sched& S, const Epi& E) {
;     ...
;         if constexpr (ALIGN_EPI) { if (wr == 0) PG8_BAR; }
;         if constexpr (!Epi::AFTER_DRAIN) { E(acc, cur, wr, wc, fr, fq); S.done(cur); }
;         if (!has_next) break;
; #pragma unroll
;         for (int a = 0; a < 2; ++a)
; #pragma unroll
;             for (int b = 0; b < 2; ++b)
; #pragma unroll
;                 for (int m = 0; m < 4; ++m)
; #pragma unroll
;                     for (int n = 0; n < 2; ++n) acc[a][b][m][n] = (f32x4){0.f, 0.f, 0.f, 0.f};
;         cur = nxt; cA = nA; cB = nB; ++ui;
;         if constexpr (ALIGN_EPI) { if (wr == 1) PG8_BAR; }
;     }
	s_andn2_b64 vcc, exec, s[16:17]
	s_cbranch_vccnz .LBB0_3332
	s_barrier
	s_branch .LBB0_3332

; __device__ __forceinline__ unsigned cvt_pk_bf16(float lo, float hi) { unsigned r; asm volatile("v_cvt_pk_bf16_f32 %0, %1, %2" : "=v"(r) : "v"(lo), "v"(hi)); return r; }
; __device__ __forceinline__ float row_rstd16_coop(const float* ssq, int row, int fq, float inv_n) {
;     const f32x4 a = *(const f32x4*)(ssq + (size_t)row * 16 + fq * 4);
;     float s = (a[0] + a[1]) + (a[2] + a[3]);
;     s += __shfl_xor(s, 16); s += __shfl_xor(s, 32);
;     return __builtin_amdgcn_rsqf(s * inv_n + EPS);
;     __device__ __forceinline__ void operator()(const f32x4 (&acc)[2][2][4][2], const Unit& u, int wr, int wc, int fr, int fq) const {
;         const int row0 = u.pm * BM + wr * 64 + fr, col0 = u.pn * BM + wc * 32 + 8 * fq;
;         float rsv[2][4];
; #pragma unroll
;         for (int ai = 0; ai < 2; ++ai) {
; #pragma unroll
;             for (int m = 0; m < 4; ++m) rsv[ai][m] = ssq ? row_rstd16_coop(ssq, row0 + ai * HALF + m * 16, fq, 1.0f / 1024.0f) : 1.0f;
;         }
; #pragma unroll
;         for (int ai = 0; ai < 2; ++ai)
; #pragma unroll
;             for (int m = 0; m < 4; ++m) {
;                 const int row = row0 + ai * HALF + m * 16;
;                 const float rs = rsv[ai][m];
;                 bf16_t* rowp = O + (size_t)row * ldc + col0;
; #pragma unroll
;                 for (int bj = 0; bj < 2; ++bj) {
;                     const f32x4 v0 = acc[ai][bj][m][0] * rs, v1 = acc[ai][bj][m][1] * rs;
;                     u32x4 w; w.x = cvt_pk_bf16(v0[0], v0[1]); w.y = cvt_pk_bf16(v0[2], v0[3]); w.z = cvt_pk_bf16(v1[0], v1[1]); w.w = cvt_pk_bf16(v1[2], v1[3]);
;                     *(u32x4*)(rowp + bj * HALF) = w;
.LBB0_4583:
	v_lshl_add_u32 v160, s52, 8, v1
	v_ashrrev_i32_e32 v161, 31, v160
	v_lshlrev_b64 v[130:131], 6, v[160:161]
	v_lshl_add_u64 v[130:131], v[142:143], 0, v[130:131]
	global_load_dwordx4 v[180:183], v[130:131], off offset:1024
	global_load_dwordx4 v[184:187], v[130:131], off offset:2048
	global_load_dwordx4 v[188:191], v[130:131], off offset:3072
	v_add_co_u32_e32 v208, vcc, 0x2000, v130
	s_nop 1
	v_addc_co_u32_e32 v209, vcc, 0, v131, vcc
	global_load_dwordx4 v[192:195], v[208:209], off
	global_load_dwordx4 v[196:199], v[208:209], off offset:1024
	global_load_dwordx4 v[200:203], v[208:209], off offset:2048
	global_load_dwordx4 v[204:207], v[208:209], off offset:3072
	global_load_dwordx4 v[130:133], v[130:131], off
	v_or_b32_e32 v164, 16, v160
	v_ashrrev_i32_e32 v165, 31, v164
	v_or_b32_e32 v166, 32, v160
	v_ashrrev_i32_e32 v167, 31, v166
	v_or_b32_e32 v168, 48, v160
	v_ashrrev_i32_e32 v169, 31, v168
	v_add_u32_e32 v170, 0x80, v160
	v_ashrrev_i32_e32 v171, 31, v170
	v_add_u32_e32 v172, 0x90, v160
	v_ashrrev_i32_e32 v173, 31, v172
	v_add_u32_e32 v174, 0xa0, v160
	v_ashrrev_i32_e32 v175, 31, v174
	v_add_u32_e32 v176, 0xb0, v160
	v_ashrrev_i32_e32 v177, 31, v176
	v_lshlrev_b64 v[160:161], 11, v[160:161]
	v_lshl_add_u64 v[160:161], s[16:17], 0, v[160:161]
	s_mov_b64 s[24:25], -1
	s_and_b64 vcc, exec, s[4:5]
	s_waitcnt vmcnt(0)
	v_mov_b32_e32 v154, v131
	v_mov_b32_e32 v155, v132
	v_mov_b32_e32 v131, v133
	v_pk_add_f32 v[130:131], v[154:155], v[130:131]
	s_nop 0
	v_add_f32_e32 v130, v130, v131
	ds_bpermute_b32 v131, v221, v130
	s_waitcnt lgkmcnt(0)
	v_add_f32_e32 v130, v130, v131
	ds_bpermute_b32 v131, v222, v130
	s_waitcnt lgkmcnt(0)
	v_add_f32_e32 v130, v130, v131
	v_fmamk_f32 v130, v130, 0x3a800000, v231
	v_rsq_f32_e32 v148, v130
	s_nop 1
	v_pk_mul_f32 v[128:129], v[128:129], v[148:149] op_sel_hi:[1,0]
	v_pk_mul_f32 v[126:127], v[126:127], v[148:149] op_sel_hi:[1,0]
	v_pk_mul_f32 v[120:121], v[120:121], v[148:149] op_sel_hi:[1,0]
	v_pk_mul_f32 v[118:119], v[118:119], v[148:149] op_sel_hi:[1,0]
	v_add_f32_e32 v130, v181, v180
	v_add_f32_e32 v131, v182, v183
	s_nop 0
	v_add_f32_e32 v130, v130, v131
	ds_bpermute_b32 v131, v221, v130
	s_waitcnt lgkmcnt(0)
	v_add_f32_e32 v130, v130, v131
	ds_bpermute_b32 v131, v222, v130
	s_waitcnt lgkmcnt(0)
	v_add_f32_e32 v130, v130, v131
	v_fmamk_f32 v130, v130, 0x3a800000, v231
	v_rsq_f32_e32 v150, v130
	s_nop 1
	v_pk_mul_f32 v[112:113], v[112:113], v[150:151] op_sel_hi:[1,0]
	v_pk_mul_f32 v[110:111], v[110:111], v[150:151] op_sel_hi:[1,0]
	v_pk_mul_f32 v[104:105], v[104:105], v[150:151] op_sel_hi:[1,0]
	v_pk_mul_f32 v[102:103], v[102:103], v[150:151] op_sel_hi:[1,0]
	v_add_f32_e32 v130, v185, v184
	v_add_f32_e32 v131, v186, v187
	s_nop 0
	v_add_f32_e32 v130, v130, v131
	ds_bpermute_b32 v131, v221, v130
	s_waitcnt lgkmcnt(0)
	v_add_f32_e32 v130, v130, v131
	ds_bpermute_b32 v131, v222, v130
	s_waitcnt lgkmcnt(0)
	v_add_f32_e32 v130, v130, v131
	v_fmamk_f32 v130, v130, 0x3a800000, v231
	v_rsq_f32_e32 v152, v130
	s_nop 1
	v_pk_mul_f32 v[96:97], v[96:97], v[152:153] op_sel_hi:[1,0]
	v_pk_mul_f32 v[94:95], v[94:95], v[152:153] op_sel_hi:[1,0]
	v_pk_mul_f32 v[88:89], v[88:89], v[152:153] op_sel_hi:[1,0]
	v_pk_mul_f32 v[86:87], v[86:87], v[152:153] op_sel_hi:[1,0]
	v_add_f32_e32 v130, v189, v188
	v_add_f32_e32 v131, v190, v191
	s_nop 0
	v_add_f32_e32 v130, v130, v131
	ds_bpermute_b32 v131, v221, v130
	s_waitcnt lgkmcnt(0)
	v_add_f32_e32 v130, v130, v131
	ds_bpermute_b32 v131, v222, v130
	s_waitcnt lgkmcnt(0)
	v_add_f32_e32 v130, v130, v131
	v_fmamk_f32 v130, v130, 0x3a800000, v231
	v_rsq_f32_e32 v154, v130
	s_nop 1
	v_pk_mul_f32 v[80:81], v[80:81], v[154:155] op_sel_hi:[1,0]
	v_pk_mul_f32 v[78:79], v[78:79], v[154:155] op_sel_hi:[1,0]
	v_pk_mul_f32 v[72:73], v[72:73], v[154:155] op_sel_hi:[1,0]
	v_pk_mul_f32 v[70:71], v[70:71], v[154:155] op_sel_hi:[1,0]
	v_add_f32_e32 v130, v193, v192
	v_add_f32_e32 v131, v194, v195
	s_nop 0
	v_add_f32_e32 v130, v130, v131
	ds_bpermute_b32 v131, v221, v130
	s_waitcnt lgkmcnt(0)
	v_add_f32_e32 v130, v130, v131
	ds_bpermute_b32 v131, v222, v130
	s_waitcnt lgkmcnt(0)
	v_add_f32_e32 v130, v130, v131
	v_fmamk_f32 v130, v130, 0x3a800000, v231
	v_rsq_f32_e32 v156, v130
	s_nop 1
	v_pk_mul_f32 v[64:65], v[64:65], v[156:157] op_sel_hi:[1,0]
	v_pk_mul_f32 v[62:63], v[62:63], v[156:157] op_sel_hi:[1,0]
	v_pk_mul_f32 v[56:57], v[56:57], v[156:157] op_sel_hi:[1,0]
	v_pk_mul_f32 v[54:55], v[54:55], v[156:157] op_sel_hi:[1,0]
	v_add_f32_e32 v130, v197, v196
	v_add_f32_e32 v131, v198, v199
	s_nop 0
	v_add_f32_e32 v130, v130, v131
	ds_bpermute_b32 v131, v221, v130
	s_waitcnt lgkmcnt(0)
	v_add_f32_e32 v130, v130, v131
	ds_bpermute_b32 v131, v222, v130
	s_waitcnt lgkmcnt(0)
	v_add_f32_e32 v130, v130, v131
	v_fmamk_f32 v130, v130, 0x3a800000, v231
	v_rsq_f32_e32 v158, v130
	s_nop 1
	v_pk_mul_f32 v[48:49], v[48:49], v[158:159] op_sel_hi:[1,0]
	v_pk_mul_f32 v[46:47], v[46:47], v[158:159] op_sel_hi:[1,0]
	v_pk_mul_f32 v[40:41], v[40:41], v[158:159] op_sel_hi:[1,0]
	v_pk_mul_f32 v[38:39], v[38:39], v[158:159] op_sel_hi:[1,0]
	v_add_f32_e32 v130, v201, v200
	v_add_f32_e32 v131, v202, v203
	s_nop 0
	v_add_f32_e32 v130, v130, v131
	ds_bpermute_b32 v131, v221, v130
	s_waitcnt lgkmcnt(0)
	v_add_f32_e32 v130, v130, v131
	ds_bpermute_b32 v131, v222, v130
	s_waitcnt lgkmcnt(0)
	v_add_f32_e32 v130, v130, v131
	v_fmamk_f32 v130, v130, 0x3a800000, v231
	v_rsq_f32_e32 v162, v130
	s_nop 1
	v_mov_b32_e32 v130, v204
	v_mov_b32_e32 v131, v205
	v_mov_b32_e32 v132, v206
	v_mov_b32_e32 v133, v207
	v_pk_mul_f32 v[32:33], v[32:33], v[162:163] op_sel_hi:[1,0]
	v_pk_mul_f32 v[30:31], v[30:31], v[162:163] op_sel_hi:[1,0]
	v_pk_mul_f32 v[24:25], v[24:25], v[162:163] op_sel_hi:[1,0]
	v_pk_mul_f32 v[22:23], v[22:23], v[162:163] op_sel_hi:[1,0]
	s_waitcnt vmcnt(0)
; __device__ __forceinline__ unsigned cvt_pk_bf16(float lo, float hi) { unsigned r; asm volatile("v_cvt_pk_bf16_f32 %0, %1, %2" : "=v"(r) : "v"(lo), "v"(hi)); return r; }
;     __device__ __forceinline__ void operator()(const f32x4 (&acc)[2][2][4][2], const Unit& u, int wr, int wc, int fr, int fq) const {
;         const int row0 = u.pm * BM + wr * 64 + fr, col0 = u.pn * BM + wc * 32 + 8 * fq;
;         float rsv[2][4];
; #pragma unroll
;         for (int ai = 0; ai < 2; ++ai) {
; #pragma unroll
;             for (int m = 0; m < 4; ++m) rsv[ai][m] = ssq ? row_rstd16_coop(ssq, row0 + ai * HALF + m * 16, fq, 1.0f / 1024.0f) : 1.0f;
;         }
; #pragma unroll
;         for (int ai = 0; ai < 2; ++ai)
; #pragma unroll
;             for (int m = 0; m < 4; ++m) {
;                 const int row = row0 + ai * HALF + m * 16;
;                 const float rs = rsv[ai][m];
;                 bf16_t* rowp = O + (size_t)row * ldc + col0;
; #pragma unroll
;                 for (int bj = 0; bj < 2; ++bj) {
;                     const f32x4 v0 = acc[ai][bj][m][0] * rs, v1 = acc[ai][bj][m][1] * rs;
;                     u32x4 w; w.x = cvt_pk_bf16(v0[0], v0[1]); w.y = cvt_pk_bf16(v0[2], v0[3]); w.z = cvt_pk_bf16(v1[0], v1[1]); w.w = cvt_pk_bf16(v1[2], v1[3]);
;                     *(u32x4*)(rowp + bj * HALF) = w;
;                 }
;             }
	v_mov_b32_e32 v179, v132
	v_lshl_or_b32 v132, s51, 8, v151
	v_mov_b32_e32 v178, v131
	v_mov_b32_e32 v131, v133
	v_ashrrev_i32_e32 v133, 31, v132
	v_lshlrev_b64 v[132:133], 1, v[132:133]
	v_pk_add_f32 v[130:131], v[178:179], v[130:131]
	v_lshl_add_u64 v[160:161], v[160:161], 0, v[132:133]
	v_pk_mul_f32 v[178:179], v[124:125], v[148:149] op_sel_hi:[1,0]
	v_pk_mul_f32 v[124:125], v[122:123], v[148:149] op_sel_hi:[1,0]
	v_cvt_pk_bf16_f32 v122, v126, v127
	v_cvt_pk_bf16_f32 v123, v128, v129
	v_add_f32_e32 v130, v130, v131
	v_cvt_pk_bf16_f32 v124, v124, v125
	v_cvt_pk_bf16_f32 v125, v178, v179
	global_store_dwordx4 v[160:161], v[122:125], off
	ds_bpermute_b32 v131, v221, v130
	s_waitcnt lgkmcnt(0)
	v_add_f32_e32 v130, v130, v131
	v_pk_mul_f32 v[122:123], v[116:117], v[148:149] op_sel_hi:[1,0]
	v_pk_mul_f32 v[116:117], v[114:115], v[148:149] op_sel_hi:[1,0]
	v_cvt_pk_bf16_f32 v114, v118, v119
	v_cvt_pk_bf16_f32 v115, v120, v121
	ds_bpermute_b32 v131, v222, v130
	v_cvt_pk_bf16_f32 v116, v116, v117
	v_cvt_pk_bf16_f32 v117, v122, v123
	global_store_dwordx4 v[160:161], v[114:117], off offset:256
	s_waitcnt lgkmcnt(0)
	v_add_f32_e32 v130, v130, v131
	v_lshlrev_b64 v[114:115], 11, v[164:165]
	v_lshl_add_u64 v[114:115], s[16:17], 0, v[114:115]
	v_lshl_add_u64 v[114:115], v[114:115], 0, v[132:133]
	v_pk_mul_f32 v[116:117], v[108:109], v[150:151] op_sel_hi:[1,0]
	v_pk_mul_f32 v[108:109], v[106:107], v[150:151] op_sel_hi:[1,0]
	v_cvt_pk_bf16_f32 v106, v110, v111
	v_cvt_pk_bf16_f32 v107, v112, v113
	v_fmamk_f32 v130, v130, 0x3a800000, v231
	v_cvt_pk_bf16_f32 v108, v108, v109
	v_cvt_pk_bf16_f32 v109, v116, v117
	global_store_dwordx4 v[114:115], v[106:109], off
	v_rsq_f32_e32 v130, v130
	s_nop 0
	v_pk_mul_f32 v[106:107], v[100:101], v[150:151] op_sel_hi:[1,0]
	v_pk_mul_f32 v[100:101], v[98:99], v[150:151] op_sel_hi:[1,0]
	v_cvt_pk_bf16_f32 v98, v102, v103
	v_cvt_pk_bf16_f32 v99, v104, v105
	v_pk_mul_f32 v[16:17], v[16:17], v[130:131] op_sel_hi:[1,0]
	v_cvt_pk_bf16_f32 v100, v100, v101
	v_cvt_pk_bf16_f32 v101, v106, v107
	global_store_dwordx4 v[114:115], v[98:101], off offset:256
	v_pk_mul_f32 v[14:15], v[14:15], v[130:131] op_sel_hi:[1,0]
	v_pk_mul_f32 v[8:9], v[8:9], v[130:131] op_sel_hi:[1,0]
	v_lshlrev_b64 v[98:99], 11, v[166:167]
	v_lshl_add_u64 v[98:99], s[16:17], 0, v[98:99]
	v_lshl_add_u64 v[98:99], v[98:99], 0, v[132:133]
	v_pk_mul_f32 v[100:101], v[92:93], v[152:153] op_sel_hi:[1,0]
	v_pk_mul_f32 v[92:93], v[90:91], v[152:153] op_sel_hi:[1,0]
	v_cvt_pk_bf16_f32 v90, v94, v95
	v_cvt_pk_bf16_f32 v91, v96, v97
	v_pk_mul_f32 v[6:7], v[6:7], v[130:131] op_sel_hi:[1,0]
	v_cvt_pk_bf16_f32 v92, v92, v93
	v_cvt_pk_bf16_f32 v93, v100, v101
	global_store_dwordx4 v[98:99], v[90:93], off
	s_nop 1
	v_pk_mul_f32 v[90:91], v[84:85], v[152:153] op_sel_hi:[1,0]
	v_pk_mul_f32 v[84:85], v[82:83], v[152:153] op_sel_hi:[1,0]
	v_cvt_pk_bf16_f32 v82, v86, v87
	v_cvt_pk_bf16_f32 v83, v88, v89
	s_nop 0
	v_cvt_pk_bf16_f32 v84, v84, v85
	v_cvt_pk_bf16_f32 v85, v90, v91
	global_store_dwordx4 v[98:99], v[82:85], off offset:256
	s_nop 1
	v_lshlrev_b64 v[82:83], 11, v[168:169]
	v_lshl_add_u64 v[82:83], s[16:17], 0, v[82:83]
	v_lshl_add_u64 v[82:83], v[82:83], 0, v[132:133]
	v_pk_mul_f32 v[84:85], v[76:77], v[154:155] op_sel_hi:[1,0]
	v_pk_mul_f32 v[76:77], v[74:75], v[154:155] op_sel_hi:[1,0]
	v_cvt_pk_bf16_f32 v74, v78, v79
	v_cvt_pk_bf16_f32 v75, v80, v81
	s_nop 0
	v_cvt_pk_bf16_f32 v76, v76, v77
	v_cvt_pk_bf16_f32 v77, v84, v85
	global_store_dwordx4 v[82:83], v[74:77], off
	s_nop 1
	v_pk_mul_f32 v[74:75], v[68:69], v[154:155] op_sel_hi:[1,0]
	v_pk_mul_f32 v[68:69], v[66:67], v[154:155] op_sel_hi:[1,0]
	v_cvt_pk_bf16_f32 v66, v70, v71
	v_cvt_pk_bf16_f32 v67, v72, v73
	s_nop 0
	v_cvt_pk_bf16_f32 v68, v68, v69
	v_cvt_pk_bf16_f32 v69, v74, v75
	global_store_dwordx4 v[82:83], v[66:69], off offset:256
	s_nop 1
	v_lshlrev_b64 v[66:67], 11, v[170:171]
	v_lshl_add_u64 v[66:67], s[16:17], 0, v[66:67]
	v_lshl_add_u64 v[66:67], v[66:67], 0, v[132:133]
	v_pk_mul_f32 v[68:69], v[60:61], v[156:157] op_sel_hi:[1,0]
	v_pk_mul_f32 v[60:61], v[58:59], v[156:157] op_sel_hi:[1,0]
	v_cvt_pk_bf16_f32 v58, v62, v63
	v_cvt_pk_bf16_f32 v59, v64, v65
	s_nop 0
	v_cvt_pk_bf16_f32 v60, v60, v61
	v_cvt_pk_bf16_f32 v61, v68, v69
	global_store_dwordx4 v[66:67], v[58:61], off
	s_nop 1
	v_pk_mul_f32 v[58:59], v[52:53], v[156:157] op_sel_hi:[1,0]
	v_pk_mul_f32 v[52:53], v[50:51], v[156:157] op_sel_hi:[1,0]
	v_cvt_pk_bf16_f32 v50, v54, v55
	v_cvt_pk_bf16_f32 v51, v56, v57
	s_nop 0
	v_cvt_pk_bf16_f32 v52, v52, v53
	v_cvt_pk_bf16_f32 v53, v58, v59
	global_store_dwordx4 v[66:67], v[50:53], off offset:256
	s_nop 1
	v_lshlrev_b64 v[50:51], 11, v[172:173]
	v_lshl_add_u64 v[50:51], s[16:17], 0, v[50:51]
	v_lshl_add_u64 v[50:51], v[50:51], 0, v[132:133]
	v_pk_mul_f32 v[52:53], v[44:45], v[158:159] op_sel_hi:[1,0]
	v_pk_mul_f32 v[44:45], v[42:43], v[158:159] op_sel_hi:[1,0]
	v_cvt_pk_bf16_f32 v42, v46, v47
	v_cvt_pk_bf16_f32 v43, v48, v49
	s_nop 0
	v_cvt_pk_bf16_f32 v44, v44, v45
	v_cvt_pk_bf16_f32 v45, v52, v53
	global_store_dwordx4 v[50:51], v[42:45], off
	s_nop 1
	v_pk_mul_f32 v[42:43], v[36:37], v[158:159] op_sel_hi:[1,0]
	v_pk_mul_f32 v[36:37], v[34:35], v[158:159] op_sel_hi:[1,0]
	v_cvt_pk_bf16_f32 v34, v38, v39
	v_cvt_pk_bf16_f32 v35, v40, v41
	s_nop 0
	v_cvt_pk_bf16_f32 v36, v36, v37
	v_cvt_pk_bf16_f32 v37, v42, v43
	global_store_dwordx4 v[50:51], v[34:37], off offset:256
	s_nop 1
	v_lshlrev_b64 v[34:35], 11, v[174:175]
	v_lshl_add_u64 v[34:35], s[16:17], 0, v[34:35]
	v_lshl_add_u64 v[34:35], v[34:35], 0, v[132:133]
	v_pk_mul_f32 v[36:37], v[28:29], v[162:163] op_sel_hi:[1,0]
	v_pk_mul_f32 v[28:29], v[26:27], v[162:163] op_sel_hi:[1,0]
	v_cvt_pk_bf16_f32 v26, v30, v31
	v_cvt_pk_bf16_f32 v27, v32, v33
	s_nop 0
	v_cvt_pk_bf16_f32 v28, v28, v29
	v_cvt_pk_bf16_f32 v29, v36, v37
	global_store_dwordx4 v[34:35], v[26:29], off
	s_nop 1
	v_pk_mul_f32 v[26:27], v[20:21], v[162:163] op_sel_hi:[1,0]
	v_pk_mul_f32 v[20:21], v[18:19], v[162:163] op_sel_hi:[1,0]
	v_cvt_pk_bf16_f32 v18, v22, v23
	v_cvt_pk_bf16_f32 v19, v24, v25
	s_nop 0
	v_cvt_pk_bf16_f32 v20, v20, v21
	v_cvt_pk_bf16_f32 v21, v26, v27
	global_store_dwordx4 v[34:35], v[18:21], off offset:256
	s_nop 1
	v_lshlrev_b64 v[18:19], 11, v[176:177]
	v_lshl_add_u64 v[18:19], s[16:17], 0, v[18:19]
	v_lshl_add_u64 v[18:19], v[18:19], 0, v[132:133]
	v_pk_mul_f32 v[20:21], v[12:13], v[130:131] op_sel_hi:[1,0]
	v_pk_mul_f32 v[12:13], v[10:11], v[130:131] op_sel_hi:[1,0]
	v_cvt_pk_bf16_f32 v10, v14, v15
	v_cvt_pk_bf16_f32 v11, v16, v17
	s_nop 0
	v_cvt_pk_bf16_f32 v12, v12, v13
	v_cvt_pk_bf16_f32 v13, v20, v21
	global_store_dwordx4 v[18:19], v[10:13], off
	s_nop 1
	v_pk_mul_f32 v[10:11], v[4:5], v[130:131] op_sel_hi:[1,0]
	v_pk_mul_f32 v[4:5], v[2:3], v[130:131] op_sel_hi:[1,0]
	v_cvt_pk_bf16_f32 v2, v6, v7
	v_cvt_pk_bf16_f32 v3, v8, v9
	s_nop 0
	v_cvt_pk_bf16_f32 v4, v4, v5
	v_cvt_pk_bf16_f32 v5, v10, v11
	global_store_dwordx4 v[18:19], v[2:5], off offset:256
	s_cbranch_vccnz .LBB0_4567
; #define PG8_BAR __builtin_amdgcn_s_barrier()
; template <class Epi, class Sched, bool ALIGN_EPI = false, bool SP2 = false>
; __device__ __forceinline__ void gemm_phase(PG8_LAS unsigned char* lds, const Gemm g, const Sched& S, const Epi& E) {
;     ...
;         if constexpr (ALIGN_EPI) { if (wr == 0) PG8_BAR; }
;         if constexpr (!Epi::AFTER_DRAIN) { E(acc, cur, wr, wc, fr, fq); S.done(cur); }
;         if (!has_next) break;
; #pragma unroll
;         for (int a = 0; a < 2; ++a)
; #pragma unroll
;             for (int b = 0; b < 2; ++b)
; #pragma unroll
;                 for (int m = 0; m < 4; ++m)
; #pragma unroll
;                     for (int n = 0; n < 2; ++n) acc[a][b][m][n] = (f32x4){0.f, 0.f, 0.f, 0.f};
;         cur = nxt; cA = nA; cB = nB; ++ui;
;         if constexpr (ALIGN_EPI) { if (wr == 1) PG8_BAR; }
;     }
	s_andn2_b64 vcc, exec, s[14:15]
	s_cbranch_vccnz .LBB0_4566
	s_barrier
	s_branch .LBB0_4566

; __device__ __forceinline__ float row_rstd16_coop(const float* ssq, int row, int fq, float inv_n) {
;     const f32x4 a = *(const f32x4*)(ssq + (size_t)row * 16 + fq * 4);
;     float s = (a[0] + a[1]) + (a[2] + a[3]);
;     s += __shfl_xor(s, 16); s += __shfl_xor(s, 32);
;     return __builtin_amdgcn_rsqf(s * inv_n + EPS);
;     __device__ __forceinline__ void operator()(const f32x4 (&acc)[2][2][4][2], const Unit& u, int wr, int wc, int fr, int fq) const {
;     ...
;         for (int ai = 0; ai < 2; ++ai) {
; #pragma unroll
;             for (int m = 0; m < 4; ++m) rsv[ai][m] = row_rstd16_coop(ssq, row0 + ai * HALF + m * 16, fq, 1.0f / 1024.0f);
;         }
; #pragma unroll
;         for (int ai = 0; ai < 2; ++ai)
; #pragma unroll
;             for (int m = 0; m < 4; ++m) {
;                 const int row = row0 + ai * HALF + m * 16;
;                 const float rs = rsv[ai][m];
;                 bf16_t* rowp = H + (size_t)row * ldh + (col0 >> 1);
; #pragma unroll
;                 for (int bj = 0; bj < 2; ++bj) {
;                     const f32x4 v0 = acc[ai][bj][m][0] * rs, v1 = acc[ai][bj][m][1] * rs;
.LBB0_4848:
	v_lshl_add_u32 v156, s52, 8, v1
	v_ashrrev_i32_e32 v157, 31, v156
	v_lshlrev_b64 v[130:131], 6, v[156:157]
	v_lshl_add_u64 v[130:131], v[142:143], 0, v[130:131]
	global_load_dwordx4 v[182:185], v[130:131], off offset:1024
	global_load_dwordx4 v[186:189], v[130:131], off offset:2048
	global_load_dwordx4 v[190:193], v[130:131], off offset:3072
	v_add_co_u32_e32 v210, vcc, 0x2000, v130
	s_nop 1
	v_addc_co_u32_e32 v211, vcc, 0, v131, vcc
	global_load_dwordx4 v[194:197], v[210:211], off
	global_load_dwordx4 v[198:201], v[210:211], off offset:1024
	global_load_dwordx4 v[202:205], v[210:211], off offset:2048
	global_load_dwordx4 v[206:209], v[210:211], off offset:3072
	global_load_dwordx4 v[130:133], v[130:131], off
	v_or_b32_e32 v174, 16, v156
	v_ashrrev_i32_e32 v175, 31, v174
	v_or_b32_e32 v170, 32, v156
	v_ashrrev_i32_e32 v171, 31, v170
	v_or_b32_e32 v166, 48, v156
	v_ashrrev_i32_e32 v167, 31, v166
	v_add_u32_e32 v162, 0x80, v156
	v_ashrrev_i32_e32 v163, 31, v162
	v_add_u32_e32 v158, 0x90, v156
	v_ashrrev_i32_e32 v159, 31, v158
	v_add_u32_e32 v152, 0xa0, v156
	v_ashrrev_i32_e32 v153, 31, v152
	s_and_b64 vcc, exec, s[4:5]
	s_waitcnt vmcnt(0)
	v_mov_b32_e32 v148, v131
	v_mov_b32_e32 v149, v132
	v_mov_b32_e32 v131, v133
	v_pk_add_f32 v[130:131], v[148:149], v[130:131]
	s_nop 0
	v_add_f32_e32 v130, v130, v131
	ds_bpermute_b32 v131, v221, v130
	s_waitcnt lgkmcnt(0)
	v_add_f32_e32 v130, v130, v131
	ds_bpermute_b32 v131, v222, v130
	s_waitcnt lgkmcnt(0)
	v_add_f32_e32 v130, v130, v131
	v_fmamk_f32 v130, v130, 0x3a800000, v231
	v_rsq_f32_e32 v176, v130
	s_nop 1
	v_pk_mul_f32 v[122:123], v[122:123], v[176:177] op_sel_hi:[1,0]
	v_pk_mul_f32 v[124:125], v[124:125], v[176:177] op_sel_hi:[1,0]
	v_pk_mul_f32 v[126:127], v[126:127], v[176:177] op_sel_hi:[1,0]
	v_pk_mul_f32 v[128:129], v[128:129], v[176:177] op_sel_hi:[1,0]
	v_pk_mul_f32 v[118:119], v[118:119], v[176:177] op_sel_hi:[1,0]
	v_pk_mul_f32 v[120:121], v[120:121], v[176:177] op_sel_hi:[1,0]
	v_pk_mul_f32 v[114:115], v[114:115], v[176:177] op_sel_hi:[1,0]
	v_pk_mul_f32 v[116:117], v[116:117], v[176:177] op_sel_hi:[1,0]
	v_add_f32_e32 v130, v183, v182
	v_add_f32_e32 v131, v184, v185
	s_nop 0
	v_add_f32_e32 v130, v130, v131
	ds_bpermute_b32 v131, v221, v130
	s_waitcnt lgkmcnt(0)
	v_add_f32_e32 v130, v130, v131
	ds_bpermute_b32 v131, v222, v130
	s_waitcnt lgkmcnt(0)
	v_add_f32_e32 v130, v130, v131
	v_fmamk_f32 v130, v130, 0x3a800000, v231
	v_rsq_f32_e32 v172, v130
	s_nop 1
	v_pk_mul_f32 v[110:111], v[110:111], v[172:173] op_sel_hi:[1,0]
	v_pk_mul_f32 v[112:113], v[112:113], v[172:173] op_sel_hi:[1,0]
	v_pk_mul_f32 v[106:107], v[106:107], v[172:173] op_sel_hi:[1,0]
	v_pk_mul_f32 v[108:109], v[108:109], v[172:173] op_sel_hi:[1,0]
	v_pk_mul_f32 v[102:103], v[102:103], v[172:173] op_sel_hi:[1,0]
	v_pk_mul_f32 v[104:105], v[104:105], v[172:173] op_sel_hi:[1,0]
	v_pk_mul_f32 v[98:99], v[98:99], v[172:173] op_sel_hi:[1,0]
	v_pk_mul_f32 v[100:101], v[100:101], v[172:173] op_sel_hi:[1,0]
	v_add_f32_e32 v130, v187, v186
	v_add_f32_e32 v131, v188, v189
	s_nop 0
	v_add_f32_e32 v130, v130, v131
	ds_bpermute_b32 v131, v221, v130
	s_waitcnt lgkmcnt(0)
	v_add_f32_e32 v130, v130, v131
	ds_bpermute_b32 v131, v222, v130
	s_waitcnt lgkmcnt(0)
	v_add_f32_e32 v130, v130, v131
	v_fmamk_f32 v130, v130, 0x3a800000, v231
	v_rsq_f32_e32 v168, v130
	s_nop 1
	v_pk_mul_f32 v[94:95], v[94:95], v[168:169] op_sel_hi:[1,0]
	v_pk_mul_f32 v[96:97], v[96:97], v[168:169] op_sel_hi:[1,0]
	v_pk_mul_f32 v[90:91], v[90:91], v[168:169] op_sel_hi:[1,0]
	v_pk_mul_f32 v[92:93], v[92:93], v[168:169] op_sel_hi:[1,0]
	v_pk_mul_f32 v[86:87], v[86:87], v[168:169] op_sel_hi:[1,0]
	v_pk_mul_f32 v[88:89], v[88:89], v[168:169] op_sel_hi:[1,0]
	v_pk_mul_f32 v[82:83], v[82:83], v[168:169] op_sel_hi:[1,0]
	v_pk_mul_f32 v[84:85], v[84:85], v[168:169] op_sel_hi:[1,0]
	v_add_f32_e32 v130, v191, v190
	v_add_f32_e32 v131, v192, v193
	s_nop 0
	v_add_f32_e32 v130, v130, v131
	ds_bpermute_b32 v131, v221, v130
	s_waitcnt lgkmcnt(0)
	v_add_f32_e32 v130, v130, v131
	ds_bpermute_b32 v131, v222, v130
	s_waitcnt lgkmcnt(0)
	v_add_f32_e32 v130, v130, v131
	v_fmamk_f32 v130, v130, 0x3a800000, v231
	v_rsq_f32_e32 v164, v130
	s_nop 1
	v_pk_mul_f32 v[78:79], v[78:79], v[164:165] op_sel_hi:[1,0]
	v_pk_mul_f32 v[80:81], v[80:81], v[164:165] op_sel_hi:[1,0]
	v_pk_mul_f32 v[74:75], v[74:75], v[164:165] op_sel_hi:[1,0]
	v_pk_mul_f32 v[76:77], v[76:77], v[164:165] op_sel_hi:[1,0]
	v_pk_mul_f32 v[70:71], v[70:71], v[164:165] op_sel_hi:[1,0]
	v_pk_mul_f32 v[72:73], v[72:73], v[164:165] op_sel_hi:[1,0]
	v_pk_mul_f32 v[66:67], v[66:67], v[164:165] op_sel_hi:[1,0]
	v_pk_mul_f32 v[68:69], v[68:69], v[164:165] op_sel_hi:[1,0]
	v_add_f32_e32 v130, v195, v194
	v_add_f32_e32 v131, v196, v197
	s_nop 0
	v_add_f32_e32 v130, v130, v131
	ds_bpermute_b32 v131, v221, v130
	s_waitcnt lgkmcnt(0)
	v_add_f32_e32 v130, v130, v131
	ds_bpermute_b32 v131, v222, v130
	s_waitcnt lgkmcnt(0)
	v_add_f32_e32 v130, v130, v131
	v_fmamk_f32 v130, v130, 0x3a800000, v231
	v_rsq_f32_e32 v160, v130
	s_nop 1
	v_pk_mul_f32 v[62:63], v[62:63], v[160:161] op_sel_hi:[1,0]
	v_pk_mul_f32 v[64:65], v[64:65], v[160:161] op_sel_hi:[1,0]
	v_pk_mul_f32 v[58:59], v[58:59], v[160:161] op_sel_hi:[1,0]
	v_pk_mul_f32 v[60:61], v[60:61], v[160:161] op_sel_hi:[1,0]
	v_pk_mul_f32 v[54:55], v[54:55], v[160:161] op_sel_hi:[1,0]
	v_pk_mul_f32 v[56:57], v[56:57], v[160:161] op_sel_hi:[1,0]
	v_pk_mul_f32 v[50:51], v[50:51], v[160:161] op_sel_hi:[1,0]
	v_pk_mul_f32 v[52:53], v[52:53], v[160:161] op_sel_hi:[1,0]
	v_add_f32_e32 v130, v199, v198
	v_add_f32_e32 v131, v200, v201
	s_nop 0
	v_add_f32_e32 v130, v130, v131
	ds_bpermute_b32 v131, v221, v130
	s_waitcnt lgkmcnt(0)
; __device__ __forceinline__ unsigned cvt_pk_bf16(float lo, float hi) { unsigned r; asm volatile("v_cvt_pk_bf16_f32 %0, %1, %2" : "=v"(r) : "v"(lo), "v"(hi)); return r; }
; __device__ __forceinline__ float row_rstd16_coop(const float* ssq, int row, int fq, float inv_n) {
;     const f32x4 a = *(const f32x4*)(ssq + (size_t)row * 16 + fq * 4);
;     float s = (a[0] + a[1]) + (a[2] + a[3]);
;     s += __shfl_xor(s, 16); s += __shfl_xor(s, 32);
;     return __builtin_amdgcn_rsqf(s * inv_n + EPS);
;     __device__ __forceinline__ static float sg(float g, float uu) { return g * __builtin_amdgcn_rcpf(1.0f + __builtin_amdgcn_exp2f(-1.4426950408889634f * g)) * uu; }
;     __device__ __forceinline__ void operator()(const f32x4 (&acc)[2][2][4][2], const Unit& u, int wr, int wc, int fr, int fq) const {
;         const int row0 = u.pm * BM + wr * 64 + fr, col0 = u.pn * BM + wc * 32 + 8 * fq;
;         float rsv[2][4];
; #pragma unroll
;         for (int ai = 0; ai < 2; ++ai) {
; #pragma unroll
;             for (int m = 0; m < 4; ++m) rsv[ai][m] = row_rstd16_coop(ssq, row0 + ai * HALF + m * 16, fq, 1.0f / 1024.0f);
;         }
; #pragma unroll
;         for (int ai = 0; ai < 2; ++ai)
; #pragma unroll
;             for (int m = 0; m < 4; ++m) {
;                 const int row = row0 + ai * HALF + m * 16;
;                 const float rs = rsv[ai][m];
;                 bf16_t* rowp = H + (size_t)row * ldh + (col0 >> 1);
; #pragma unroll
;                 for (int bj = 0; bj < 2; ++bj) {
;                     const f32x4 v0 = acc[ai][bj][m][0] * rs, v1 = acc[ai][bj][m][1] * rs;
;                     u32x2 w; w.x = cvt_pk_bf16(sg(v0[0], v0[1]), sg(v0[2], v0[3])); w.y = cvt_pk_bf16(sg(v1[0], v1[1]), sg(v1[2], v1[3]));
;                     *(u32x2*)(rowp + bj * (HALF / 2)) = w;
;                 }
;             }
	v_add_f32_e32 v130, v130, v131
	ds_bpermute_b32 v131, v222, v130
	s_waitcnt lgkmcnt(0)
	v_add_f32_e32 v130, v130, v131
	v_fmamk_f32 v130, v130, 0x3a800000, v231
	v_rsq_f32_e32 v154, v130
	s_nop 1
	v_pk_mul_f32 v[46:47], v[46:47], v[154:155] op_sel_hi:[1,0]
	v_pk_mul_f32 v[48:49], v[48:49], v[154:155] op_sel_hi:[1,0]
	v_pk_mul_f32 v[42:43], v[42:43], v[154:155] op_sel_hi:[1,0]
	v_pk_mul_f32 v[44:45], v[44:45], v[154:155] op_sel_hi:[1,0]
	v_pk_mul_f32 v[38:39], v[38:39], v[154:155] op_sel_hi:[1,0]
	v_pk_mul_f32 v[40:41], v[40:41], v[154:155] op_sel_hi:[1,0]
	v_pk_mul_f32 v[34:35], v[34:35], v[154:155] op_sel_hi:[1,0]
	v_pk_mul_f32 v[36:37], v[36:37], v[154:155] op_sel_hi:[1,0]
	v_add_f32_e32 v130, v203, v202
	v_add_f32_e32 v131, v204, v205
	v_add_u32_e32 v148, 0xb0, v156
	v_add_f32_e32 v130, v130, v131
	ds_bpermute_b32 v131, v221, v130
	v_ashrrev_i32_e32 v149, 31, v148
	s_waitcnt lgkmcnt(0)
	v_add_f32_e32 v130, v130, v131
	ds_bpermute_b32 v131, v222, v130
	s_waitcnt lgkmcnt(0)
	v_add_f32_e32 v130, v130, v131
	v_fmamk_f32 v130, v130, 0x3a800000, v231
	v_rsq_f32_e32 v150, v130
	s_nop 1
	v_pk_mul_f32 v[30:31], v[30:31], v[150:151] op_sel_hi:[1,0]
	v_pk_mul_f32 v[32:33], v[32:33], v[150:151] op_sel_hi:[1,0]
	v_pk_mul_f32 v[26:27], v[26:27], v[150:151] op_sel_hi:[1,0]
	v_pk_mul_f32 v[28:29], v[28:29], v[150:151] op_sel_hi:[1,0]
	v_pk_mul_f32 v[22:23], v[22:23], v[150:151] op_sel_hi:[1,0]
	v_pk_mul_f32 v[24:25], v[24:25], v[150:151] op_sel_hi:[1,0]
	v_pk_mul_f32 v[18:19], v[18:19], v[150:151] op_sel_hi:[1,0]
	v_pk_mul_f32 v[20:21], v[20:21], v[150:151] op_sel_hi:[1,0]
	v_add_f32_e32 v130, v207, v206
	v_add_f32_e32 v131, v208, v209
	v_mov_b64_e32 v[132:133], s[16:17]
	v_add_f32_e32 v130, v130, v131
	ds_bpermute_b32 v131, v221, v130
	v_mad_i64_i32 v[180:181], s[24:25], v156, s96, v[132:133]
	s_waitcnt lgkmcnt(0)
	v_add_f32_e32 v130, v130, v131
	ds_bpermute_b32 v131, v222, v130
	s_waitcnt lgkmcnt(0)
	v_add_f32_e32 v130, v130, v131
	v_lshl_or_b32 v131, s51, 8, v155
	v_ashrrev_i32_e32 v178, 1, v131
	v_mul_f32_e32 v131, 0xbfb8aa3b, v122
	v_exp_f32_e32 v131, v131
	v_ashrrev_i32_e32 v179, 31, v178
	v_lshlrev_b64 v[156:157], 1, v[178:179]
	v_lshl_add_u64 v[178:179], v[180:181], 0, v[156:157]
	v_add_f32_e32 v131, 1.0, v131
	v_rcp_f32_e32 v131, v131
	v_fmamk_f32 v130, v130, 0x3a800000, v231
	v_rsq_f32_e32 v130, v130
	v_mul_f32_e32 v122, v122, v131
	v_mul_f32_e32 v122, v123, v122
	v_mul_f32_e32 v123, 0xbfb8aa3b, v124
	v_exp_f32_e32 v123, v123
	v_pk_mul_f32 v[14:15], v[14:15], v[130:131] op_sel_hi:[1,0]
	v_pk_mul_f32 v[16:17], v[16:17], v[130:131] op_sel_hi:[1,0]
	v_pk_mul_f32 v[10:11], v[10:11], v[130:131] op_sel_hi:[1,0]
	v_add_f32_e32 v123, 1.0, v123
	v_rcp_f32_e32 v123, v123
	v_pk_mul_f32 v[12:13], v[12:13], v[130:131] op_sel_hi:[1,0]
	v_pk_mul_f32 v[6:7], v[6:7], v[130:131] op_sel_hi:[1,0]
	v_pk_mul_f32 v[8:9], v[8:9], v[130:131] op_sel_hi:[1,0]
	v_mul_f32_e32 v123, v124, v123
	v_mul_f32_e32 v123, v125, v123
	v_cvt_pk_bf16_f32 v122, v122, v123
	v_mul_f32_e32 v123, 0xbfb8aa3b, v126
	v_exp_f32_e32 v123, v123
	v_mul_f32_e32 v124, 0xbfb8aa3b, v128
	v_exp_f32_e32 v124, v124
	v_pk_mul_f32 v[2:3], v[2:3], v[130:131] op_sel_hi:[1,0]
	v_add_f32_e32 v123, 1.0, v123
	v_rcp_f32_e32 v123, v123
	v_add_f32_e32 v124, 1.0, v124
	v_rcp_f32_e32 v124, v124
	v_pk_mul_f32 v[4:5], v[4:5], v[130:131] op_sel_hi:[1,0]
	v_mul_f32_e32 v123, v126, v123
	v_mul_f32_e32 v123, v127, v123
	v_mul_f32_e32 v124, v128, v124
	v_mul_f32_e32 v124, v129, v124
	v_cvt_pk_bf16_f32 v123, v123, v124
	global_store_dwordx2 v[178:179], v[122:123], off
	v_mul_f32_e32 v122, 0xbfb8aa3b, v118
	v_exp_f32_e32 v122, v122
	s_nop 0
	v_add_f32_e32 v122, 1.0, v122
	v_rcp_f32_e32 v122, v122
	s_nop 0
	v_mul_f32_e32 v118, v118, v122
	v_mul_f32_e32 v118, v119, v118
	v_mul_f32_e32 v119, 0xbfb8aa3b, v120
	v_exp_f32_e32 v119, v119
	s_nop 0
	v_add_f32_e32 v119, 1.0, v119
	v_rcp_f32_e32 v119, v119
	s_nop 0
	v_mul_f32_e32 v119, v120, v119
	v_mul_f32_e32 v119, v121, v119
	v_cvt_pk_bf16_f32 v118, v118, v119
	v_mul_f32_e32 v119, 0xbfb8aa3b, v114
	v_exp_f32_e32 v119, v119
	s_nop 0
	v_add_f32_e32 v119, 1.0, v119
	v_rcp_f32_e32 v119, v119
	s_nop 0
	v_mul_f32_e32 v114, v114, v119
	v_mul_f32_e32 v114, v115, v114
	v_mul_f32_e32 v115, 0xbfb8aa3b, v116
	v_exp_f32_e32 v115, v115
	s_nop 0
	v_add_f32_e32 v115, 1.0, v115
	v_rcp_f32_e32 v115, v115
	s_nop 0
	v_mul_f32_e32 v115, v116, v115
	v_mul_f32_e32 v116, 0xbfb8aa3b, v110
	v_exp_f32_e32 v116, v116
	v_mul_f32_e32 v115, v117, v115
	v_cvt_pk_bf16_f32 v119, v114, v115
	global_store_dwordx2 v[178:179], v[118:119], off offset:128
	v_add_f32_e32 v116, 1.0, v116
	v_rcp_f32_e32 v116, v116
	v_mad_i64_i32 v[114:115], s[24:25], v174, s96, v[132:133]
	v_lshl_add_u64 v[114:115], v[114:115], 0, v[156:157]
	v_mul_f32_e32 v110, v110, v116
	v_mul_f32_e32 v110, v111, v110
	v_mul_f32_e32 v111, 0xbfb8aa3b, v112
	v_exp_f32_e32 v111, v111
	s_nop 0
	v_add_f32_e32 v111, 1.0, v111
	v_rcp_f32_e32 v111, v111
	s_nop 0
	v_mul_f32_e32 v111, v112, v111
	v_mul_f32_e32 v111, v113, v111
	v_cvt_pk_bf16_f32 v110, v110, v111
	v_mul_f32_e32 v111, 0xbfb8aa3b, v106
	v_exp_f32_e32 v111, v111
	s_nop 0
	v_add_f32_e32 v111, 1.0, v111
	v_rcp_f32_e32 v111, v111
	s_nop 0
	v_mul_f32_e32 v106, v106, v111
	v_mul_f32_e32 v106, v107, v106
	v_mul_f32_e32 v107, 0xbfb8aa3b, v108
	v_exp_f32_e32 v107, v107
	s_nop 0
	v_add_f32_e32 v107, 1.0, v107
	v_rcp_f32_e32 v107, v107
	s_nop 0
	v_mul_f32_e32 v107, v108, v107
	v_mul_f32_e32 v107, v109, v107
	v_cvt_pk_bf16_f32 v111, v106, v107
	v_mul_f32_e32 v106, 0xbfb8aa3b, v102
	v_exp_f32_e32 v106, v106
	global_store_dwordx2 v[114:115], v[110:111], off
	v_add_f32_e32 v106, 1.0, v106
	v_rcp_f32_e32 v106, v106
; __device__ __forceinline__ unsigned cvt_pk_bf16(float lo, float hi) { unsigned r; asm volatile("v_cvt_pk_bf16_f32 %0, %1, %2" : "=v"(r) : "v"(lo), "v"(hi)); return r; }
;     __device__ __forceinline__ static float sg(float g, float uu) { return g * __builtin_amdgcn_rcpf(1.0f + __builtin_amdgcn_exp2f(-1.4426950408889634f * g)) * uu; }
;     __device__ __forceinline__ void operator()(const f32x4 (&acc)[2][2][4][2], const Unit& u, int wr, int wc, int fr, int fq) const {
;         const int row0 = u.pm * BM + wr * 64 + fr, col0 = u.pn * BM + wc * 32 + 8 * fq;
;         float rsv[2][4];
; #pragma unroll
;         for (int ai = 0; ai < 2; ++ai) {
; #pragma unroll
;             for (int m = 0; m < 4; ++m) rsv[ai][m] = row_rstd16_coop(ssq, row0 + ai * HALF + m * 16, fq, 1.0f / 1024.0f);
;         }
; #pragma unroll
;         for (int ai = 0; ai < 2; ++ai)
; #pragma unroll
;             for (int m = 0; m < 4; ++m) {
;                 const int row = row0 + ai * HALF + m * 16;
;                 const float rs = rsv[ai][m];
;                 bf16_t* rowp = H + (size_t)row * ldh + (col0 >> 1);
; #pragma unroll
;                 for (int bj = 0; bj < 2; ++bj) {
;                     const f32x4 v0 = acc[ai][bj][m][0] * rs, v1 = acc[ai][bj][m][1] * rs;
;                     u32x2 w; w.x = cvt_pk_bf16(sg(v0[0], v0[1]), sg(v0[2], v0[3])); w.y = cvt_pk_bf16(sg(v1[0], v1[1]), sg(v1[2], v1[3]));
;                     *(u32x2*)(rowp + bj * (HALF / 2)) = w;
;                 }
	s_nop 0
	v_mul_f32_e32 v102, v102, v106
	v_mul_f32_e32 v102, v103, v102
	v_mul_f32_e32 v103, 0xbfb8aa3b, v104
	v_exp_f32_e32 v103, v103
	s_nop 0
	v_add_f32_e32 v103, 1.0, v103
	v_rcp_f32_e32 v103, v103
	s_nop 0
	v_mul_f32_e32 v103, v104, v103
	v_mul_f32_e32 v103, v105, v103
	v_cvt_pk_bf16_f32 v102, v102, v103
	v_mul_f32_e32 v103, 0xbfb8aa3b, v98
	v_exp_f32_e32 v103, v103
	s_nop 0
	v_add_f32_e32 v103, 1.0, v103
	v_rcp_f32_e32 v103, v103
	s_nop 0
	v_mul_f32_e32 v98, v98, v103
	v_mul_f32_e32 v98, v99, v98
	v_mul_f32_e32 v99, 0xbfb8aa3b, v100
	v_exp_f32_e32 v99, v99
	s_nop 0
	v_add_f32_e32 v99, 1.0, v99
	v_rcp_f32_e32 v99, v99
	s_nop 0
	v_mul_f32_e32 v99, v100, v99
	v_mul_f32_e32 v100, 0xbfb8aa3b, v94
	v_exp_f32_e32 v100, v100
	v_mul_f32_e32 v99, v101, v99
	v_cvt_pk_bf16_f32 v103, v98, v99
	global_store_dwordx2 v[114:115], v[102:103], off offset:128
	v_add_f32_e32 v100, 1.0, v100
	v_rcp_f32_e32 v100, v100
	v_mad_i64_i32 v[98:99], s[24:25], v170, s96, v[132:133]
	v_lshl_add_u64 v[98:99], v[98:99], 0, v[156:157]
	v_mul_f32_e32 v94, v94, v100
	v_mul_f32_e32 v94, v95, v94
	v_mul_f32_e32 v95, 0xbfb8aa3b, v96
	v_exp_f32_e32 v95, v95
	s_nop 0
	v_add_f32_e32 v95, 1.0, v95
	v_rcp_f32_e32 v95, v95
	s_nop 0
	v_mul_f32_e32 v95, v96, v95
	v_mul_f32_e32 v95, v97, v95
	v_cvt_pk_bf16_f32 v94, v94, v95
	v_mul_f32_e32 v95, 0xbfb8aa3b, v90
	v_exp_f32_e32 v95, v95
	s_nop 0
	v_add_f32_e32 v95, 1.0, v95
	v_rcp_f32_e32 v95, v95
	s_nop 0
	v_mul_f32_e32 v90, v90, v95
	v_mul_f32_e32 v90, v91, v90
	v_mul_f32_e32 v91, 0xbfb8aa3b, v92
	v_exp_f32_e32 v91, v91
	s_nop 0
	v_add_f32_e32 v91, 1.0, v91
	v_rcp_f32_e32 v91, v91
	s_nop 0
	v_mul_f32_e32 v91, v92, v91
	v_mul_f32_e32 v91, v93, v91
	v_cvt_pk_bf16_f32 v95, v90, v91
	v_mul_f32_e32 v90, 0xbfb8aa3b, v86
	v_exp_f32_e32 v90, v90
	global_store_dwordx2 v[98:99], v[94:95], off
	v_add_f32_e32 v90, 1.0, v90
	v_rcp_f32_e32 v90, v90
	s_nop 0
	v_mul_f32_e32 v86, v86, v90
	v_mul_f32_e32 v86, v87, v86
	v_mul_f32_e32 v87, 0xbfb8aa3b, v88
	v_exp_f32_e32 v87, v87
	s_nop 0
	v_add_f32_e32 v87, 1.0, v87
	v_rcp_f32_e32 v87, v87
	s_nop 0
	v_mul_f32_e32 v87, v88, v87
	v_mul_f32_e32 v87, v89, v87
	v_cvt_pk_bf16_f32 v86, v86, v87
	v_mul_f32_e32 v87, 0xbfb8aa3b, v82
	v_exp_f32_e32 v87, v87
	s_nop 0
	v_add_f32_e32 v87, 1.0, v87
	v_rcp_f32_e32 v87, v87
	s_nop 0
	v_mul_f32_e32 v82, v82, v87
	v_mul_f32_e32 v82, v83, v82
	v_mul_f32_e32 v83, 0xbfb8aa3b, v84
	v_exp_f32_e32 v83, v83
	s_nop 0
	v_add_f32_e32 v83, 1.0, v83
	v_rcp_f32_e32 v83, v83
	s_nop 0
	v_mul_f32_e32 v83, v84, v83
	v_mul_f32_e32 v84, 0xbfb8aa3b, v78
	v_exp_f32_e32 v84, v84
	v_mul_f32_e32 v83, v85, v83
	v_cvt_pk_bf16_f32 v87, v82, v83
	global_store_dwordx2 v[98:99], v[86:87], off offset:128
	v_add_f32_e32 v84, 1.0, v84
	v_rcp_f32_e32 v84, v84
	v_mad_i64_i32 v[82:83], s[24:25], v166, s96, v[132:133]
	v_lshl_add_u64 v[82:83], v[82:83], 0, v[156:157]
	v_mul_f32_e32 v78, v78, v84
	v_mul_f32_e32 v78, v79, v78
	v_mul_f32_e32 v79, 0xbfb8aa3b, v80
	v_exp_f32_e32 v79, v79
	s_nop 0
	v_add_f32_e32 v79, 1.0, v79
	v_rcp_f32_e32 v79, v79
	s_nop 0
	v_mul_f32_e32 v79, v80, v79
	v_mul_f32_e32 v79, v81, v79
	v_cvt_pk_bf16_f32 v78, v78, v79
	v_mul_f32_e32 v79, 0xbfb8aa3b, v74
	v_exp_f32_e32 v79, v79
	s_nop 0
	v_add_f32_e32 v79, 1.0, v79
	v_rcp_f32_e32 v79, v79
	s_nop 0
	v_mul_f32_e32 v74, v74, v79
	v_mul_f32_e32 v74, v75, v74
	v_mul_f32_e32 v75, 0xbfb8aa3b, v76
	v_exp_f32_e32 v75, v75
	s_nop 0
	v_add_f32_e32 v75, 1.0, v75
	v_rcp_f32_e32 v75, v75
	s_nop 0
	v_mul_f32_e32 v75, v76, v75
	v_mul_f32_e32 v75, v77, v75
	v_cvt_pk_bf16_f32 v79, v74, v75
	v_mul_f32_e32 v74, 0xbfb8aa3b, v70
	v_exp_f32_e32 v74, v74
	global_store_dwordx2 v[82:83], v[78:79], off
	v_add_f32_e32 v74, 1.0, v74
	v_rcp_f32_e32 v74, v74
	s_nop 0
	v_mul_f32_e32 v70, v70, v74
	v_mul_f32_e32 v70, v71, v70
	v_mul_f32_e32 v71, 0xbfb8aa3b, v72
	v_exp_f32_e32 v71, v71
	s_nop 0
	v_add_f32_e32 v71, 1.0, v71
	v_rcp_f32_e32 v71, v71
	s_nop 0
	v_mul_f32_e32 v71, v72, v71
	v_mul_f32_e32 v71, v73, v71
	v_cvt_pk_bf16_f32 v70, v70, v71
	v_mul_f32_e32 v71, 0xbfb8aa3b, v66
	v_exp_f32_e32 v71, v71
	s_nop 0
	v_add_f32_e32 v71, 1.0, v71
	v_rcp_f32_e32 v71, v71
	s_nop 0
	v_mul_f32_e32 v66, v66, v71
	v_mul_f32_e32 v66, v67, v66
	v_mul_f32_e32 v67, 0xbfb8aa3b, v68
	v_exp_f32_e32 v67, v67
	s_nop 0
	v_add_f32_e32 v67, 1.0, v67
	v_rcp_f32_e32 v67, v67
	s_nop 0
	v_mul_f32_e32 v67, v68, v67
	v_mul_f32_e32 v68, 0xbfb8aa3b, v62
	v_exp_f32_e32 v68, v68
	v_mul_f32_e32 v67, v69, v67
	v_cvt_pk_bf16_f32 v71, v66, v67
	global_store_dwordx2 v[82:83], v[70:71], off offset:128
	v_add_f32_e32 v68, 1.0, v68
	v_rcp_f32_e32 v68, v68
	v_mad_i64_i32 v[66:67], s[24:25], v162, s96, v[132:133]
	v_lshl_add_u64 v[66:67], v[66:67], 0, v[156:157]
	v_mul_f32_e32 v62, v62, v68
	v_mul_f32_e32 v62, v63, v62
	v_mul_f32_e32 v63, 0xbfb8aa3b, v64
	v_exp_f32_e32 v63, v63
	s_nop 0
	v_add_f32_e32 v63, 1.0, v63
	v_rcp_f32_e32 v63, v63
	s_nop 0
	v_mul_f32_e32 v63, v64, v63
	v_mul_f32_e32 v63, v65, v63
	v_cvt_pk_bf16_f32 v62, v62, v63
	v_mul_f32_e32 v63, 0xbfb8aa3b, v58
	v_exp_f32_e32 v63, v63
	s_nop 0
	v_add_f32_e32 v63, 1.0, v63
	v_rcp_f32_e32 v63, v63
	s_nop 0
	v_mul_f32_e32 v58, v58, v63
	v_mul_f32_e32 v58, v59, v58
	v_mul_f32_e32 v59, 0xbfb8aa3b, v60
	v_exp_f32_e32 v59, v59
	s_nop 0
	v_add_f32_e32 v59, 1.0, v59
	v_rcp_f32_e32 v59, v59
	s_nop 0
	v_mul_f32_e32 v59, v60, v59
	v_mul_f32_e32 v59, v61, v59
	v_cvt_pk_bf16_f32 v63, v58, v59
	v_mul_f32_e32 v58, 0xbfb8aa3b, v54
	v_exp_f32_e32 v58, v58
	global_store_dwordx2 v[66:67], v[62:63], off
	v_add_f32_e32 v58, 1.0, v58
	v_rcp_f32_e32 v58, v58
	s_nop 0
	v_mul_f32_e32 v54, v54, v58
	v_mul_f32_e32 v54, v55, v54
	v_mul_f32_e32 v55, 0xbfb8aa3b, v56
; __device__ __forceinline__ unsigned cvt_pk_bf16(float lo, float hi) { unsigned r; asm volatile("v_cvt_pk_bf16_f32 %0, %1, %2" : "=v"(r) : "v"(lo), "v"(hi)); return r; }
; #define PG8_BAR __builtin_amdgcn_s_barrier()
;     __device__ __forceinline__ static float sg(float g, float uu) { return g * __builtin_amdgcn_rcpf(1.0f + __builtin_amdgcn_exp2f(-1.4426950408889634f * g)) * uu; }
; template <class Epi, class Sched, bool ALIGN_EPI = false, bool SP2 = false>
; __device__ __forceinline__ void gemm_phase(PG8_LAS unsigned char* lds, const Gemm g, const Sched& S, const Epi& E) {
;     ...
;         if constexpr (ALIGN_EPI) { if (wr == 0) PG8_BAR; }
;         if constexpr (!Epi::AFTER_DRAIN) { E(acc, cur, wr, wc, fr, fq); S.done(cur); }
;         if (!has_next) break;
; #pragma unroll
;         for (int a = 0; a < 2; ++a)
; #pragma unroll
;             for (int b = 0; b < 2; ++b)
; #pragma unroll
;                 for (int m = 0; m < 4; ++m)
; #pragma unroll
;                     for (int n = 0; n < 2; ++n) acc[a][b][m][n] = (f32x4){0.f, 0.f, 0.f, 0.f};
;         cur = nxt; cA = nA; cB = nB; ++ui;
;         if constexpr (ALIGN_EPI) { if (wr == 1) PG8_BAR; }
;     __device__ __forceinline__ void operator()(const f32x4 (&acc)[2][2][4][2], const Unit& u, int wr, int wc, int fr, int fq) const {
;     ...
;         for (int ai = 0; ai < 2; ++ai)
; #pragma unroll
;             for (int m = 0; m < 4; ++m) {
;                 const int row = row0 + ai * HALF + m * 16;
;                 const float rs = rsv[ai][m];
;                 bf16_t* rowp = H + (size_t)row * ldh + (col0 >> 1);
; #pragma unroll
;                 for (int bj = 0; bj < 2; ++bj) {
;                     const f32x4 v0 = acc[ai][bj][m][0] * rs, v1 = acc[ai][bj][m][1] * rs;
;                     u32x2 w; w.x = cvt_pk_bf16(sg(v0[0], v0[1]), sg(v0[2], v0[3])); w.y = cvt_pk_bf16(sg(v1[0], v1[1]), sg(v1[2], v1[3]));
;                     *(u32x2*)(rowp + bj * (HALF / 2)) = w;
;                 }
;             }
	v_exp_f32_e32 v55, v55
	s_nop 0
	v_add_f32_e32 v55, 1.0, v55
	v_rcp_f32_e32 v55, v55
	s_nop 0
	v_mul_f32_e32 v55, v56, v55
	v_mul_f32_e32 v55, v57, v55
	v_cvt_pk_bf16_f32 v54, v54, v55
	v_mul_f32_e32 v55, 0xbfb8aa3b, v50
	v_exp_f32_e32 v55, v55
	s_nop 0
	v_add_f32_e32 v55, 1.0, v55
	v_rcp_f32_e32 v55, v55
	s_nop 0
	v_mul_f32_e32 v50, v50, v55
	v_mul_f32_e32 v50, v51, v50
	v_mul_f32_e32 v51, 0xbfb8aa3b, v52
	v_exp_f32_e32 v51, v51
	s_nop 0
	v_add_f32_e32 v51, 1.0, v51
	v_rcp_f32_e32 v51, v51
	s_nop 0
	v_mul_f32_e32 v51, v52, v51
	v_mul_f32_e32 v52, 0xbfb8aa3b, v46
	v_exp_f32_e32 v52, v52
	v_mul_f32_e32 v51, v53, v51
	v_cvt_pk_bf16_f32 v55, v50, v51
	global_store_dwordx2 v[66:67], v[54:55], off offset:128
	v_add_f32_e32 v52, 1.0, v52
	v_rcp_f32_e32 v52, v52
	v_mad_i64_i32 v[50:51], s[24:25], v158, s96, v[132:133]
	v_lshl_add_u64 v[50:51], v[50:51], 0, v[156:157]
	v_mul_f32_e32 v46, v46, v52
	v_mul_f32_e32 v46, v47, v46
	v_mul_f32_e32 v47, 0xbfb8aa3b, v48
	v_exp_f32_e32 v47, v47
	s_nop 0
	v_add_f32_e32 v47, 1.0, v47
	v_rcp_f32_e32 v47, v47
	s_nop 0
	v_mul_f32_e32 v47, v48, v47
	v_mul_f32_e32 v47, v49, v47
	v_cvt_pk_bf16_f32 v46, v46, v47
	v_mul_f32_e32 v47, 0xbfb8aa3b, v42
	v_exp_f32_e32 v47, v47
	s_nop 0
	v_add_f32_e32 v47, 1.0, v47
	v_rcp_f32_e32 v47, v47
	s_nop 0
	v_mul_f32_e32 v42, v42, v47
	v_mul_f32_e32 v42, v43, v42
	v_mul_f32_e32 v43, 0xbfb8aa3b, v44
	v_exp_f32_e32 v43, v43
	s_nop 0
	v_add_f32_e32 v43, 1.0, v43
	v_rcp_f32_e32 v43, v43
	s_nop 0
	v_mul_f32_e32 v43, v44, v43
	v_mul_f32_e32 v43, v45, v43
	v_cvt_pk_bf16_f32 v47, v42, v43
	v_mul_f32_e32 v42, 0xbfb8aa3b, v38
	v_exp_f32_e32 v42, v42
	global_store_dwordx2 v[50:51], v[46:47], off
	v_add_f32_e32 v42, 1.0, v42
	v_rcp_f32_e32 v42, v42
	s_nop 0
	v_mul_f32_e32 v38, v38, v42
	v_mul_f32_e32 v38, v39, v38
	v_mul_f32_e32 v39, 0xbfb8aa3b, v40
	v_exp_f32_e32 v39, v39
	s_nop 0
	v_add_f32_e32 v39, 1.0, v39
	v_rcp_f32_e32 v39, v39
	s_nop 0
	v_mul_f32_e32 v39, v40, v39
	v_mul_f32_e32 v39, v41, v39
	v_cvt_pk_bf16_f32 v38, v38, v39
	v_mul_f32_e32 v39, 0xbfb8aa3b, v34
	v_exp_f32_e32 v39, v39
	s_nop 0
	v_add_f32_e32 v39, 1.0, v39
	v_rcp_f32_e32 v39, v39
	s_nop 0
	v_mul_f32_e32 v34, v34, v39
	v_mul_f32_e32 v34, v35, v34
	v_mul_f32_e32 v35, 0xbfb8aa3b, v36
	v_exp_f32_e32 v35, v35
	s_nop 0
	v_add_f32_e32 v35, 1.0, v35
	v_rcp_f32_e32 v35, v35
	s_nop 0
	v_mul_f32_e32 v35, v36, v35
	v_mul_f32_e32 v36, 0xbfb8aa3b, v30
	v_exp_f32_e32 v36, v36
	v_mul_f32_e32 v35, v37, v35
	v_cvt_pk_bf16_f32 v39, v34, v35
	global_store_dwordx2 v[50:51], v[38:39], off offset:128
	v_add_f32_e32 v36, 1.0, v36
	v_rcp_f32_e32 v36, v36
	v_mad_i64_i32 v[34:35], s[24:25], v152, s96, v[132:133]
	v_lshl_add_u64 v[34:35], v[34:35], 0, v[156:157]
	v_mul_f32_e32 v30, v30, v36
	v_mul_f32_e32 v30, v31, v30
	v_mul_f32_e32 v31, 0xbfb8aa3b, v32
	v_exp_f32_e32 v31, v31
	s_nop 0
	v_add_f32_e32 v31, 1.0, v31
	v_rcp_f32_e32 v31, v31
	s_nop 0
	v_mul_f32_e32 v31, v32, v31
	v_mul_f32_e32 v31, v33, v31
	v_cvt_pk_bf16_f32 v30, v30, v31
	v_mul_f32_e32 v31, 0xbfb8aa3b, v26
	v_exp_f32_e32 v31, v31
	s_nop 0
	v_add_f32_e32 v31, 1.0, v31
	v_rcp_f32_e32 v31, v31
	s_nop 0
	v_mul_f32_e32 v26, v26, v31
	v_mul_f32_e32 v26, v27, v26
	v_mul_f32_e32 v27, 0xbfb8aa3b, v28
	v_exp_f32_e32 v27, v27
	s_nop 0
	v_add_f32_e32 v27, 1.0, v27
	v_rcp_f32_e32 v27, v27
	s_nop 0
	v_mul_f32_e32 v27, v28, v27
	v_mul_f32_e32 v27, v29, v27
	v_cvt_pk_bf16_f32 v31, v26, v27
	v_mul_f32_e32 v26, 0xbfb8aa3b, v22
	v_exp_f32_e32 v26, v26
	global_store_dwordx2 v[34:35], v[30:31], off
	v_add_f32_e32 v26, 1.0, v26
	v_rcp_f32_e32 v26, v26
	s_nop 0
	v_mul_f32_e32 v22, v22, v26
	v_mul_f32_e32 v22, v23, v22
	v_mul_f32_e32 v23, 0xbfb8aa3b, v24
	v_exp_f32_e32 v23, v23
	s_nop 0
	v_add_f32_e32 v23, 1.0, v23
	v_rcp_f32_e32 v23, v23
	s_nop 0
	v_mul_f32_e32 v23, v24, v23
	v_mul_f32_e32 v23, v25, v23
	v_cvt_pk_bf16_f32 v22, v22, v23
	v_mul_f32_e32 v23, 0xbfb8aa3b, v18
	v_exp_f32_e32 v23, v23
	s_nop 0
	v_add_f32_e32 v23, 1.0, v23
	v_rcp_f32_e32 v23, v23
	s_nop 0
	v_mul_f32_e32 v18, v18, v23
	v_mul_f32_e32 v18, v19, v18
	v_mul_f32_e32 v19, 0xbfb8aa3b, v20
	v_exp_f32_e32 v19, v19
	s_nop 0
	v_add_f32_e32 v19, 1.0, v19
	v_rcp_f32_e32 v19, v19
	s_nop 0
	v_mul_f32_e32 v19, v20, v19
	v_mul_f32_e32 v20, 0xbfb8aa3b, v14
	v_exp_f32_e32 v20, v20
	v_mul_f32_e32 v19, v21, v19
	v_cvt_pk_bf16_f32 v23, v18, v19
	global_store_dwordx2 v[34:35], v[22:23], off offset:128
	v_add_f32_e32 v20, 1.0, v20
	v_rcp_f32_e32 v20, v20
	v_mad_i64_i32 v[18:19], s[24:25], v148, s96, v[132:133]
	v_lshl_add_u64 v[18:19], v[18:19], 0, v[156:157]
	v_mul_f32_e32 v14, v14, v20
	v_mul_f32_e32 v14, v15, v14
	v_mul_f32_e32 v15, 0xbfb8aa3b, v16
	v_exp_f32_e32 v15, v15
	s_mov_b64 s[24:25], -1
	v_add_f32_e32 v15, 1.0, v15
	v_rcp_f32_e32 v15, v15
	s_nop 0
	v_mul_f32_e32 v15, v16, v15
	v_mul_f32_e32 v15, v17, v15
	v_cvt_pk_bf16_f32 v14, v14, v15
	v_mul_f32_e32 v15, 0xbfb8aa3b, v10
	v_exp_f32_e32 v15, v15
	s_nop 0
	v_add_f32_e32 v15, 1.0, v15
	v_rcp_f32_e32 v15, v15
	s_nop 0
	v_mul_f32_e32 v10, v10, v15
	v_mul_f32_e32 v10, v11, v10
	v_mul_f32_e32 v11, 0xbfb8aa3b, v12
	v_exp_f32_e32 v11, v11
	s_nop 0
	v_add_f32_e32 v11, 1.0, v11
	v_rcp_f32_e32 v11, v11
	s_nop 0
	v_mul_f32_e32 v11, v12, v11
	v_mul_f32_e32 v11, v13, v11
	v_cvt_pk_bf16_f32 v15, v10, v11
	v_mul_f32_e32 v10, 0xbfb8aa3b, v6
	v_exp_f32_e32 v10, v10
	global_store_dwordx2 v[18:19], v[14:15], off
	v_add_f32_e32 v10, 1.0, v10
	v_rcp_f32_e32 v10, v10
	s_nop 0
	v_mul_f32_e32 v6, v6, v10
	v_mul_f32_e32 v6, v7, v6
	v_mul_f32_e32 v7, 0xbfb8aa3b, v8
	v_exp_f32_e32 v7, v7
	s_nop 0
	v_add_f32_e32 v7, 1.0, v7
	v_rcp_f32_e32 v7, v7
	s_nop 0
	v_mul_f32_e32 v7, v8, v7
	v_mul_f32_e32 v7, v9, v7
	v_cvt_pk_bf16_f32 v6, v6, v7
	v_mul_f32_e32 v7, 0xbfb8aa3b, v2
	v_exp_f32_e32 v7, v7
	s_nop 0
	v_add_f32_e32 v7, 1.0, v7
	v_rcp_f32_e32 v7, v7
	s_nop 0
	v_mul_f32_e32 v2, v2, v7
	v_mul_f32_e32 v2, v3, v2
	v_mul_f32_e32 v3, 0xbfb8aa3b, v4
	v_exp_f32_e32 v3, v3
	s_nop 0
	v_add_f32_e32 v3, 1.0, v3
	v_rcp_f32_e32 v3, v3
	s_nop 0
	v_mul_f32_e32 v3, v4, v3
	v_mul_f32_e32 v3, v5, v3
	v_cvt_pk_bf16_f32 v7, v2, v3
	global_store_dwordx2 v[18:19], v[6:7], off offset:128
	s_cbranch_vccnz .LBB0_4832
	s_andn2_b64 vcc, exec, s[14:15]
	s_cbranch_vccnz .LBB0_4831
	s_barrier
	s_branch .LBB0_4831
